# march: previous chunk's y rows finished under the next chunk's first tile, block-relative decay factors for off-diagonal tiles, scan moved to the single-tile Y wave
# speedup vs baseline: 1.0561x; 1.0112x over previous
.Lm_fwd_1:
	s_lshl_b32 s15, s7, 23
	s_lshl_b32 s96, s6, 22
	s_add_u32 s15, s15, s96
	s_lshl_b32 s96, s11, 16
	s_add_u32 s15, s15, s96
	s_add_u32 s15, s15, 0x1b000000
	s_add_u32 s38, s36, s15
	s_addc_u32 s39, s37, 0
	s_lshl_b32 s15, s8, 1
	s_add_u32 s15, s15, s5
	s_lshl_b32 s15, s15, 20
	s_lshl_b32 s96, s6, 19
	s_add_u32 s15, s15, s96
	s_lshl_b32 s96, s11, 13
	s_add_u32 s15, s15, s96
	s_add_u32 s15, s15, 0x17000000
	s_add_u32 s40, s36, s15
	s_addc_u32 s41, s37, 0
	s_lshl_b32 s15, s6, 21
	s_add_u32 s15, s15, s9
	s_lshl_b32 s96, s11, 15
	s_add_u32 s15, s15, s96
	s_add_u32 s15, s15, 0x1f000000
	s_add_u32 s42, s36, s15
	s_addc_u32 s43, s37, 0
	s_lshl_b32 s15, s6, 25
	s_lshl_b32 s96, s8, 7
	s_add_u32 s15, s15, s96
	s_lshl_b32 s96, s5, 6
	s_add_u32 s15, s15, s96
	s_lshl_b32 s96, s11, 19
	s_add_u32 s15, s15, s96
	s_lshl_b32 s96, s51, 26
	s_add_u32 s15, s15, s96
	s_add_u32 s15, s15, 0xf000000
	s_add_u32 s44, s36, s15
	s_addc_u32 s45, s37, 0
	s_add_u32 s4, s3, 1
	s_sub_i32 s5, 4, s3
	s_movk_i32 s6, 0x2200
	s_mov_b32 s7, 0xffffde00
	s_movk_i32 s8, 0x80
	s_mov_b32 s9, 0xffffff80
	s_movk_i32 s15, 0x800
	s_mov_b32 s96, 0xfffff800
	s_cmp_eq_u32 s51, 0
	s_cselect_b32 s52, s4, s5
	s_cselect_b32 s53, s7, s6
	s_cselect_b32 s54, s9, s8
	s_cselect_b32 s13, s96, s15
	s_cselect_b32 s21, 124, 0
	s_waitcnt lgkmcnt(0)
	v_mov_b32_e32 v1, s10
	v_mul_f32_e32 v1, 0x3fb8aa3b, v1
	v_exp_f32_e32 v1, v1
	s_nop 0
	v_xor_b32_e32 v1, 0x80000000, v1
	s_nop 0
	v_readfirstlane_b32 s62, v1
	v_and_b32_e32 v116, 31, v175
	v_bfe_u32 v117, v175, 5, 1
	v_bfe_u32 v118, v175, 2, 2
	v_and_b32_e32 v119, 3, v175
	v_bfe_u32 v120, v175, 4, 1
	v_and_b32_e32 v121, 63, v175
	v_lshlrev_b32_e32 v122, 5, v120
	v_lshl_add_u32 v122, v119, 3, v122
	v_lshl_add_u32 v123, v117, 3, v118
	s_cmp_lt_u32 s3, 4
	s_cbranch_scc0 .Lm_setup_hi_2
	s_lshl_b32 s4, s3, 5
	v_add_u32_e32 v128, s4, v116
	v_lshlrev_b32_e32 v129, 4, v117
	v_lshrrev_b32_e32 v124, 4, v121
	v_and_b32_e32 v125, 15, v121
	v_lshlrev_b32_e32 v125, 4, v125
	v_lshlrev_b32_e32 v126, 3, v124
	s_lshl_b32 s4, s3, 5
	v_add_u32_e32 v127, s4, v126
	v_lshl_add_u32 v164, v127, 9, v125
	v_add_u32_e32 v164, 0x100, v164
	s_mul_i32 s4, s3, 0x2200
	s_add_u32 s4, s4, 0x11000
	v_mad_u32_u24 v166, v126, s59, v125
	v_add_u32_e32 v166, s4, v166
	v_mad_u32_u24 v167, v116, s59, v129
	v_add_u32_e32 v167, s4, v167
	v_lshlrev_b32_e32 v130, 3, v117
	v_mov_b32_e32 v131, 80
	v_mad_u32_u24 v168, v116, v131, v130
	v_add_u32_e32 v168, s4, v168
	v_lshrrev_b32_e32 v124, 2, v121
	v_and_b32_e32 v125, 3, v121
	v_lshlrev_b32_e32 v125, 4, v125
	v_mad_u32_u24 v169, v124, v131, v125
	v_add_u32_e32 v169, s4, v169
	s_lshl_b32 s4, s3, 5
	v_add_u32_e32 v124, s4, v124
	v_lshl_add_u32 v170, v124, 12, v125
	v_add_u32_e32 v171, 0x10000, v170
	v_mad_u32_u24 v165, v128, s59, v129
	v_mad_u32_u24 v130, v116, s59, v129
	v_add_u32_e32 v210, 0x1e800, v130
	v_lshlrev_b32_e32 v130, 2, v128
	v_add_u32_e32 v211, 0x22c00, v130
	v_lshlrev_b32_e32 v130, 3, v117
	v_lshl_add_u32 v212, v128, 12, v130
	s_lshl_b32 s4, s3, 7
	s_add_u32 s4, s4, 0x22c00
	v_add_u32_e32 v217, s4, v129
	s_lshl_b32 s4, s3, 7
	s_add_u32 s4, s4, 0x1d800
	v_add_u32_e32 v172, s4, v129
	s_cmp_eq_u32 s51, 0
	s_cselect_b32 s5, 124, 0
	s_lshl_b32 s4, s3, 7
	s_add_u32 s4, s4, s5
	s_add_u32 s4, s4, 0x22c00
	v_mov_b32_e32 v209, s4
	v_lshl_add_u32 v130, v117, 2, v118
	s_lshl_b32 s4, s3, 5
	v_add_u32_e32 v130, s4, v130
	v_mad_u32_u24 v130, v130, s60, v122
	v_add_u32_e32 v222, 0x19800, v130
	v_lshlrev_b32_e32 v129, 2, v117
	s_cmp_eq_u32 s51, 0
	s_cbranch_scc0 .Lm_mbwd_4
	v_add_u32_e32 v130, 0, v129
	v_cmp_le_u32_e64 s[64:65], v130, v116
	v_add_u32_e32 v130, 1, v129
	v_cmp_le_u32_e64 s[66:67], v130, v116
	v_add_u32_e32 v130, 2, v129
	v_cmp_le_u32_e64 s[68:69], v130, v116
	v_add_u32_e32 v130, 3, v129
	v_cmp_le_u32_e64 s[70:71], v130, v116
	v_add_u32_e32 v130, 8, v129
	v_cmp_le_u32_e64 s[72:73], v130, v116
	v_add_u32_e32 v130, 9, v129
	v_cmp_le_u32_e64 s[74:75], v130, v116
	v_add_u32_e32 v130, 10, v129
	v_cmp_le_u32_e64 s[76:77], v130, v116
	v_add_u32_e32 v130, 11, v129
	v_cmp_le_u32_e64 s[78:79], v130, v116
	v_add_u32_e32 v130, 16, v129
	v_cmp_le_u32_e64 s[80:81], v130, v116
	v_add_u32_e32 v130, 17, v129
	v_cmp_le_u32_e64 s[82:83], v130, v116
	v_add_u32_e32 v130, 18, v129
	v_cmp_le_u32_e64 s[84:85], v130, v116
	v_add_u32_e32 v130, 19, v129
	v_cmp_le_u32_e64 s[86:87], v130, v116
	v_add_u32_e32 v130, 24, v129
	v_cmp_le_u32_e64 s[88:89], v130, v116
	v_add_u32_e32 v130, 25, v129
	v_cmp_le_u32_e64 s[90:91], v130, v116
	v_add_u32_e32 v130, 26, v129
	v_cmp_le_u32_e64 s[92:93], v130, v116
	v_add_u32_e32 v130, 27, v129
	v_cmp_le_u32_e64 s[94:95], v130, v116
	s_branch .Lm_mdone_5

.Lm_setup_hi_2:
	v_and_b32_e32 v126, 0xff, v175
	v_lshrrev_b32_e32 v124, 4, v126
	v_and_b32_e32 v125, 15, v126
	v_lshlrev_b32_e32 v125, 4, v125
	v_lshl_add_u32 v164, v124, 12, v125
	v_lshlrev_b32_e32 v127, 3, v124
	v_mad_u32_u24 v170, v127, s59, v125
	v_lshlrev_b32_e32 v168, 4, v126
	v_add_u32_e32 v169, 0x1000, v168
	v_lshrrev_b32_e32 v126, 2, v126
	v_lshlrev_b32_e32 v127, 4, v119
	v_mad_u32_u24 v127, v126, s60, v127
	v_add_u32_e32 v171, 0x19800, v127
	v_add_u32_e32 v197, 0x1b800, v127
	v_lshlrev_b32_e32 v127, 2, v126
	v_add_u32_e32 v172, 0x22c00, v127
	v_mov_b32_e32 v173, 0x23000
	v_mad_u32_u24 v130, v123, s60, v122
	v_add_u32_e32 v192, 0x1b800, v130
	v_mad_u32_u24 v131, v123, s59, v122
	s_sub_i32 s4, s3, 4
	s_lshl_b32 s4, s4, 6
	v_add_u32_e32 v193, s4, v131
	v_add_u32_e32 v198, 0x8800, v193
	v_lshlrev_b32_e32 v130, 3, v117
	v_mad_u32_u24 v130, v116, s59, v130
	v_add_u32_e32 v130, s4, v130
	v_add_u32_e32 v194, 0x1e800, v130
	v_lshlrev_b32_e32 v195, 9, v121
	v_lshlrev_b32_e32 v130, 3, v121
	v_add_u32_e32 v196, 0x22c00, v130
	v_add_u32_e32 v200, 0x1d800, v130
	v_lshrrev_b32_e32 v130, 4, v121
	v_lshlrev_b32_e32 v130, 7, v130
	s_cmp_eq_u32 s51, 0
	s_cselect_b32 s5, 124, 0
	s_add_u32 s5, s5, 0x22c00
	v_add_u32_e32 v199, s5, v130
	v_mov_b32_e32 v176, 0
	v_mov_b32_e32 v177, 0
	v_mov_b32_e32 v178, 0
	v_mov_b32_e32 v179, 0
	v_mov_b32_e32 v180, 0
	v_mov_b32_e32 v181, 0
	v_mov_b32_e32 v182, 0
	v_mov_b32_e32 v183, 0
	v_mov_b32_e32 v184, 0
	v_mov_b32_e32 v185, 0
	v_mov_b32_e32 v186, 0
	v_mov_b32_e32 v187, 0
	v_mov_b32_e32 v188, 0
	v_mov_b32_e32 v189, 0
	v_mov_b32_e32 v190, 0
	v_mov_b32_e32 v191, 0
.Lm_setup_done_3:
	v_lshlrev_b32_e32 v130, 4, v175
	v_add_u32_e32 v130, 0x1e800, v130
	ds_write_b128 v130, v[112:115] offset:0
	ds_write_b128 v130, v[112:115] offset:8192
	ds_write_b128 v130, v[112:115] offset:16384
	s_mov_b32 s14, 0
	s_movk_i32 s16, 1280
	s_movk_i32 s17, 2560
	s_mov_b32 s19, 0
	s_movk_i32 s20, 0x200
	s_cmp_lt_u32 s3, 4
	s_cbranch_scc0 .Lm_pro_hi_6
	s_cmp_eq_u32 s52, 1
	s_cbranch_scc0 .Lm_ys0_8
	v_and_b32_e32 v132, 63, v175
	v_lshlrev_b32_e32 v132, 9, v132
	global_load_dword v146, v132, s[42:43]
	global_load_dword v147, v132, s[42:43] offset:256
	s_add_u32 s42, s42, s48
	s_addc_u32 s43, s43, s55
.Lm_ys0_8:
	global_load_dwordx4 v[4:7], v164, s[38:39] offset:0
	global_load_dwordx4 v[8:11], v164, s[38:39] offset:512
	global_load_dwordx4 v[12:15], v164, s[38:39] offset:1024
	global_load_dwordx4 v[16:19], v164, s[38:39] offset:1536
	global_load_dwordx4 v[20:23], v164, s[38:39] offset:2048
	global_load_dwordx4 v[24:27], v164, s[38:39] offset:2560
	global_load_dwordx4 v[28:31], v164, s[38:39] offset:3072
	global_load_dwordx4 v[32:35], v164, s[38:39] offset:3584
	s_add_u32 s38, s38, s46
	s_addc_u32 s39, s39, s55
	global_load_dwordx4 v[40:43], v164, s[38:39] offset:0
	global_load_dwordx4 v[44:47], v164, s[38:39] offset:512
	global_load_dwordx4 v[48:51], v164, s[38:39] offset:1024
	global_load_dwordx4 v[52:55], v164, s[38:39] offset:1536
	global_load_dwordx4 v[56:59], v164, s[38:39] offset:2048
	global_load_dwordx4 v[60:63], v164, s[38:39] offset:2560
	global_load_dwordx4 v[64:67], v164, s[38:39] offset:3072
	global_load_dwordx4 v[68:71], v164, s[38:39] offset:3584
	s_add_u32 s38, s38, s46
	s_addc_u32 s39, s39, s55
	s_waitcnt vmcnt(8)
	ds_write_b128 v166, v[4:7] offset:0
	ds_write_b128 v166, v[8:11] offset:272
	ds_write_b128 v166, v[12:15] offset:544
	ds_write_b128 v166, v[16:19] offset:816
	ds_write_b128 v166, v[20:23] offset:1088
	ds_write_b128 v166, v[24:27] offset:1360
	ds_write_b128 v166, v[28:31] offset:1632
	ds_write_b128 v166, v[32:35] offset:1904
	global_load_dwordx4 v[4:7], v164, s[38:39] offset:0
	global_load_dwordx4 v[8:11], v164, s[38:39] offset:512
	global_load_dwordx4 v[12:15], v164, s[38:39] offset:1024
	global_load_dwordx4 v[16:19], v164, s[38:39] offset:1536
	global_load_dwordx4 v[20:23], v164, s[38:39] offset:2048
	global_load_dwordx4 v[24:27], v164, s[38:39] offset:2560
	global_load_dwordx4 v[28:31], v164, s[38:39] offset:3072
	global_load_dwordx4 v[32:35], v164, s[38:39] offset:3584
	s_add_u32 s38, s38, s46
	s_addc_u32 s39, s39, s55
	s_waitcnt vmcnt(0)
	s_cmp_eq_u32 s52, 1
	s_cbranch_scc0 .Lm_ys1_9
	v_mul_f32_e32 v132, s62, v146
	v_mul_f32_e32 v133, s62, v147
	v_add_f32_e32 v134, v132, v133
	v_and_b32_e32 v140, 63, v175
	v_lshrrev_b32_e32 v142, 4, v140
	v_add_f32_dpp v134, v134, v134 row_shr:1 row_mask:0xf bank_mask:0xf bound_ctrl:0
	s_nop 1
	v_add_f32_dpp v134, v134, v134 row_shr:2 row_mask:0xf bank_mask:0xf bound_ctrl:0
	s_nop 1
	v_add_f32_dpp v134, v134, v134 row_shr:4 row_mask:0xf bank_mask:0xf bound_ctrl:0
	s_nop 1
	v_add_f32_dpp v134, v134, v134 row_shr:8 row_mask:0xf bank_mask:0xf bound_ctrl:0
	s_nop 1
	v_add_f32_dpp v134, v134, v134 row_bcast:15 row_mask:0xa bank_mask:0xf
	s_nop 1
	v_add_f32_dpp v134, v134, v134 row_bcast:31 row_mask:0xc bank_mask:0xf
	v_lshlrev_b32_e32 v140, 3, v140
	v_lshlrev_b32_e32 v142, 7, v142
	v_readlane_b32 s97, v134, 63
	v_sub_f32_e32 v138, v134, v133
	v_mov_b32_e32 v139, v134
	v_add_u32_e32 v143, 0x1d800, v140
	v_add_u32_e32 v143, s19, v143
	s_cmp_eq_u32 s51, 0
	s_cbranch_scc1 .Lm_scanf_11
	v_sub_f32_e32 v138, s97, v138
	v_sub_f32_e32 v139, s97, v139
	v_fma_f32 v138, v146, s62, v138
	v_fma_f32 v139, v147, s62, v139
.Lm_scanf_11:
	s_add_u32 s4, s14, 0x22c00
	v_mov_b32_e32 v135, s97
	v_add_u32_e32 v140, s4, v140
	s_add_u32 s5, s4, s21
	v_add_u32_e32 v142, s5, v142
	s_add_u32 s4, s4, 0x400
	v_mov_b32_e32 v141, s4
	v_mul_f32_e32 v138, 0x3fb8aa3b, v138
	v_mul_f32_e32 v139, 0x3fb8aa3b, v139
	v_mul_f32_e32 v135, 0x3fb8aa3b, v135
	ds_write_b64 v140, v[138:139]
	ds_write_b64 v140, v[146:147] offset:512
	ds_write_b32 v141, v135
	v_mov_b32_e32 v140, v143
	s_waitcnt lgkmcnt(0)
	ds_read_b32 v143, v142
	s_waitcnt lgkmcnt(0)
	v_sub_f32_e32 v144, v143, v138
	v_sub_f32_e32 v145, v143, v139
	v_exp_f32_e32 v144, v144
	v_exp_f32_e32 v145, v145
	s_nop 0
	ds_write_b64 v140, v[144:145]
	s_waitcnt lgkmcnt(0)
	v_and_b32_e32 v132, 63, v175
	v_lshlrev_b32_e32 v132, 9, v132
	global_load_dword v146, v132, s[42:43]
	global_load_dword v147, v132, s[42:43] offset:256
	s_add_u32 s42, s42, s48
	s_addc_u32 s43, s43, s55
	s_waitcnt vmcnt(0)
.Lm_ys1_9:
	s_waitcnt lgkmcnt(0)
	s_barrier
	s_cmp_eq_u32 s52, 1
	s_cbranch_scc0 .Lm_ys2_10
	v_mul_f32_e32 v132, s62, v146
	v_mul_f32_e32 v133, s62, v147
	v_add_f32_e32 v134, v132, v133
	v_and_b32_e32 v140, 63, v175
	v_lshrrev_b32_e32 v142, 4, v140
	v_add_f32_dpp v134, v134, v134 row_shr:1 row_mask:0xf bank_mask:0xf bound_ctrl:0
	s_nop 1
	v_add_f32_dpp v134, v134, v134 row_shr:2 row_mask:0xf bank_mask:0xf bound_ctrl:0
	s_nop 1
	v_add_f32_dpp v134, v134, v134 row_shr:4 row_mask:0xf bank_mask:0xf bound_ctrl:0
	s_nop 1
	v_add_f32_dpp v134, v134, v134 row_shr:8 row_mask:0xf bank_mask:0xf bound_ctrl:0
	s_nop 1
	v_add_f32_dpp v134, v134, v134 row_bcast:15 row_mask:0xa bank_mask:0xf
	s_nop 1
	v_add_f32_dpp v134, v134, v134 row_bcast:31 row_mask:0xc bank_mask:0xf
	v_lshlrev_b32_e32 v140, 3, v140
	v_lshlrev_b32_e32 v142, 7, v142
	v_readlane_b32 s97, v134, 63
	v_sub_f32_e32 v138, v134, v133
	v_mov_b32_e32 v139, v134
	v_add_u32_e32 v143, 0x1d800, v140
	v_add_u32_e32 v143, s20, v143
	s_cmp_eq_u32 s51, 0
	s_cbranch_scc1 .Lm_scanf_12
	v_sub_f32_e32 v138, s97, v138
	v_sub_f32_e32 v139, s97, v139
	v_fma_f32 v138, v146, s62, v138
	v_fma_f32 v139, v147, s62, v139
.Lm_scanf_12:
	s_add_u32 s4, s16, 0x22c00
	v_mov_b32_e32 v135, s97
	v_add_u32_e32 v140, s4, v140
	s_add_u32 s5, s4, s21
	v_add_u32_e32 v142, s5, v142
	s_add_u32 s4, s4, 0x400
	v_mov_b32_e32 v141, s4
	v_mul_f32_e32 v138, 0x3fb8aa3b, v138
	v_mul_f32_e32 v139, 0x3fb8aa3b, v139
	v_mul_f32_e32 v135, 0x3fb8aa3b, v135
	ds_write_b64 v140, v[138:139]
	ds_write_b64 v140, v[146:147] offset:512
	ds_write_b32 v141, v135
	v_mov_b32_e32 v140, v143
	s_waitcnt lgkmcnt(0)
	ds_read_b32 v143, v142
	s_waitcnt lgkmcnt(0)
	v_sub_f32_e32 v144, v143, v138
	v_sub_f32_e32 v145, v143, v139
	v_exp_f32_e32 v144, v144
	v_exp_f32_e32 v145, v145
	s_nop 0
	ds_write_b64 v140, v[144:145]
	s_waitcnt lgkmcnt(0)
	v_and_b32_e32 v132, 63, v175
	v_lshlrev_b32_e32 v132, 9, v132
	global_load_dword v146, v132, s[42:43]
	global_load_dword v147, v132, s[42:43] offset:256
	s_add_u32 s42, s42, s48
	s_addc_u32 s43, s43, s55
.Lm_ys2_10:
	s_waitcnt lgkmcnt(0)
	s_barrier
	s_branch .Lm_pro_j_7
.Lm_pro_hi_6:
	global_load_dwordx4 v[4:7], v164, s[38:39] offset:0
	global_load_dwordx4 v[8:11], v164, s[38:39] offset:512
	global_load_dwordx4 v[12:15], v164, s[38:39] offset:1024
	global_load_dwordx4 v[16:19], v164, s[38:39] offset:1536
	global_load_dwordx4 v[20:23], v164, s[38:39] offset:2048
	global_load_dwordx4 v[24:27], v164, s[38:39] offset:2560
	global_load_dwordx4 v[28:31], v164, s[38:39] offset:3072
	global_load_dwordx4 v[32:35], v164, s[38:39] offset:3584
	global_load_dwordx4 v[36:39], v168, s[40:41]
	global_load_dwordx4 v[40:43], v169, s[40:41]
	s_add_u32 s38, s38, s46
	s_addc_u32 s39, s39, s55
	s_add_u32 s40, s40, s47
	s_addc_u32 s41, s41, s55
	global_load_dwordx4 v[44:47], v164, s[38:39] offset:0
	global_load_dwordx4 v[48:51], v164, s[38:39] offset:512
	global_load_dwordx4 v[52:55], v164, s[38:39] offset:1024
	global_load_dwordx4 v[56:59], v164, s[38:39] offset:1536
	global_load_dwordx4 v[60:63], v164, s[38:39] offset:2048
	global_load_dwordx4 v[64:67], v164, s[38:39] offset:2560
	global_load_dwordx4 v[68:71], v164, s[38:39] offset:3072
	global_load_dwordx4 v[72:75], v164, s[38:39] offset:3584
	global_load_dwordx4 v[76:79], v168, s[40:41]
	global_load_dwordx4 v[80:83], v169, s[40:41]
	s_add_u32 s38, s38, s46
	s_addc_u32 s39, s39, s55
	s_add_u32 s40, s40, s47
	s_addc_u32 s41, s41, s55
	s_waitcnt lgkmcnt(0)
	s_barrier
	s_waitcnt vmcnt(10)
	v_add_u32_e32 v154, s14, v172
	v_add_u32_e32 v155, s14, v173
	ds_read_b32 v116, v155
	ds_read_b32 v117, v154
	ds_read_b32 v118, v154 offset:512
	ds_read_b32 v152, v154 offset:256
	ds_read_b32 v153, v154 offset:768
	ds_write_b128 v170, v[4:7] offset:0
	ds_write_b128 v170, v[8:11] offset:272
	ds_write_b128 v170, v[12:15] offset:544
	ds_write_b128 v170, v[16:19] offset:816
	ds_write_b128 v170, v[20:23] offset:1088
	ds_write_b128 v170, v[24:27] offset:1360
	ds_write_b128 v170, v[28:31] offset:1632
	ds_write_b128 v170, v[32:35] offset:1904
	v_lshlrev_b32_e32 v120, 16, v36
	v_and_b32_e32 v121, 0xffff0000, v36
	v_lshlrev_b32_e32 v122, 16, v37
	v_and_b32_e32 v123, 0xffff0000, v37
	v_lshlrev_b32_e32 v124, 16, v38
	v_and_b32_e32 v125, 0xffff0000, v38
	v_lshlrev_b32_e32 v126, 16, v39
	v_and_b32_e32 v127, 0xffff0000, v39
	s_waitcnt lgkmcnt(8)
	v_sub_f32_e32 v119, v116, v117
	v_exp_f32_e32 v119, v119
	v_mul_f32_e32 v128, v118, v120
	v_mul_f32_e32 v129, v118, v121
	v_mul_f32_e32 v130, v118, v122
	v_mul_f32_e32 v131, v118, v123
	v_mul_f32_e32 v132, v118, v124
	v_mul_f32_e32 v133, v118, v125
	v_mul_f32_e32 v134, v118, v126
	v_mul_f32_e32 v135, v118, v127
	v_mul_f32_e32 v119, v118, v119
	v_cvt_pk_bf16_f32 v144, v128, v129
	v_cvt_pk_bf16_f32 v145, v130, v131
	v_cvt_pk_bf16_f32 v146, v132, v133
	v_cvt_pk_bf16_f32 v147, v134, v135
	v_mul_f32_e32 v136, v119, v120
	v_mul_f32_e32 v137, v119, v121
	v_mul_f32_e32 v138, v119, v122
	v_mul_f32_e32 v139, v119, v123
	v_mul_f32_e32 v140, v119, v124
	v_mul_f32_e32 v141, v119, v125
	v_mul_f32_e32 v142, v119, v126
	v_mul_f32_e32 v143, v119, v127
	v_cvt_pk_bf16_f32 v148, v136, v137
	v_cvt_pk_bf16_f32 v149, v138, v139
	v_cvt_pk_bf16_f32 v150, v140, v141
	v_cvt_pk_bf16_f32 v151, v142, v143
	ds_write_b128 v171, v[144:147] offset:0
	ds_write_b128 v197, v[148:151] offset:0
	v_lshlrev_b32_e32 v120, 16, v40
	v_and_b32_e32 v121, 0xffff0000, v40
	v_lshlrev_b32_e32 v122, 16, v41
	v_and_b32_e32 v123, 0xffff0000, v41
	v_lshlrev_b32_e32 v124, 16, v42
	v_and_b32_e32 v125, 0xffff0000, v42
	v_lshlrev_b32_e32 v126, 16, v43
	v_and_b32_e32 v127, 0xffff0000, v43
	v_sub_f32_e32 v119, v116, v152
	v_exp_f32_e32 v119, v119
	v_mul_f32_e32 v128, v153, v120
	v_mul_f32_e32 v129, v153, v121
	v_mul_f32_e32 v130, v153, v122
	v_mul_f32_e32 v131, v153, v123
	v_mul_f32_e32 v132, v153, v124
	v_mul_f32_e32 v133, v153, v125
	v_mul_f32_e32 v134, v153, v126
	v_mul_f32_e32 v135, v153, v127
	v_mul_f32_e32 v119, v153, v119
	v_cvt_pk_bf16_f32 v144, v128, v129
	v_cvt_pk_bf16_f32 v145, v130, v131
	v_cvt_pk_bf16_f32 v146, v132, v133
	v_cvt_pk_bf16_f32 v147, v134, v135
	v_mul_f32_e32 v136, v119, v120
	v_mul_f32_e32 v137, v119, v121
	v_mul_f32_e32 v138, v119, v122
	v_mul_f32_e32 v139, v119, v123
	v_mul_f32_e32 v140, v119, v124
	v_mul_f32_e32 v141, v119, v125
	v_mul_f32_e32 v142, v119, v126
	v_mul_f32_e32 v143, v119, v127
	v_cvt_pk_bf16_f32 v148, v136, v137
	v_cvt_pk_bf16_f32 v149, v138, v139
	v_cvt_pk_bf16_f32 v150, v140, v141
	v_cvt_pk_bf16_f32 v151, v142, v143
	ds_write_b128 v171, v[144:147] offset:4096
	ds_write_b128 v197, v[148:151] offset:4096
	global_load_dwordx4 v[4:7], v164, s[38:39] offset:0
	global_load_dwordx4 v[8:11], v164, s[38:39] offset:512
	global_load_dwordx4 v[12:15], v164, s[38:39] offset:1024
	global_load_dwordx4 v[16:19], v164, s[38:39] offset:1536
	global_load_dwordx4 v[20:23], v164, s[38:39] offset:2048
	global_load_dwordx4 v[24:27], v164, s[38:39] offset:2560
	global_load_dwordx4 v[28:31], v164, s[38:39] offset:3072
	global_load_dwordx4 v[32:35], v164, s[38:39] offset:3584
	global_load_dwordx4 v[36:39], v168, s[40:41]
	global_load_dwordx4 v[40:43], v169, s[40:41]
	s_add_u32 s38, s38, s46
	s_addc_u32 s39, s39, s55
	s_add_u32 s40, s40, s47
	s_addc_u32 s41, s41, s55
	s_waitcnt lgkmcnt(0)
	s_barrier

.Lm_loop:
	s_and_b32 s19, s50, 3
	s_lshl_b32 s19, s19, 9
	s_add_u32 s20, s50, 2
	s_and_b32 s20, s20, 3
	s_lshl_b32 s20, s20, 9
	s_cmp_lt_u32 s3, 4
	s_cbranch_scc0 .Lm_hi_13
	v_mov_b32_e32 v223, v165
	v_add_u32_e32 v224, s14, v217
	v_add_u32_e32 v208, s19, v172
	v_add_u32_e32 v216, s14, v209
	v_mov_b32_e32 v225, v222
	v_add_u32_e32 v1, s14, v211
	ds_read_b128 v[176:179], v167 offset:0
	ds_read_b128 v[180:183], v167 offset:32
	ds_read_b128 v[184:187], v167 offset:64
	ds_read_b128 v[188:191], v167 offset:96
	ds_read_b128 v[192:195], v167 offset:128
	ds_read_b128 v[196:199], v167 offset:160
	ds_read_b128 v[200:203], v167 offset:192
	ds_read_b128 v[204:207], v167 offset:224
	ds_read_b128 v[148:151], v223 offset:0
	ds_read_b128 v[152:155], v223 offset:32
	ds_read_b128 v[156:159], v223 offset:64
	ds_read_b128 v[160:163], v223 offset:96
	s_waitcnt lgkmcnt(11)
	s_waitcnt lgkmcnt(3)
	v_mfma_f32_32x32x16_bf16 v[116:131], v[148:151], v[176:179], 0
	ds_read_b128 v[148:151], v223 offset:128
	v_fma_f32 v76, v92, v3, v76
	v_fma_f32 v77, v93, v3, v77
	v_fma_f32 v78, v94, v3, v78
	s_waitcnt lgkmcnt(3)
	v_mfma_f32_32x32x16_bf16 v[116:131], v[152:155], v[180:183], v[116:131]
	ds_read_b128 v[152:155], v223 offset:160
	v_fma_f32 v79, v95, v3, v79
	v_fma_f32 v80, v96, v3, v80
	v_fma_f32 v81, v97, v3, v81
	s_waitcnt lgkmcnt(3)
	v_mfma_f32_32x32x16_bf16 v[116:131], v[156:159], v[184:187], v[116:131]
	ds_read_b128 v[156:159], v223 offset:192
	v_fma_f32 v82, v98, v3, v82
	v_fma_f32 v83, v99, v3, v83
	v_fma_f32 v84, v100, v3, v84
	s_waitcnt lgkmcnt(3)
	v_mfma_f32_32x32x16_bf16 v[116:131], v[160:163], v[188:191], v[116:131]
	ds_read_b128 v[160:163], v223 offset:224
	v_fma_f32 v85, v101, v3, v85
	v_fma_f32 v86, v102, v3, v86
	v_fma_f32 v87, v103, v3, v87
	ds_read_b128 v[234:237], v224 offset:0
	ds_read_b128 v[238:241], v224 offset:32
	ds_read_b128 v[242:245], v224 offset:64
	ds_read_b128 v[246:249], v224 offset:96
	ds_read_b32 v250, v1
	s_waitcnt lgkmcnt(8)
	v_mfma_f32_32x32x16_bf16 v[116:131], v[148:151], v[192:195], v[116:131]
	v_fma_f32 v88, v104, v3, v88
	v_fma_f32 v89, v105, v3, v89
	v_fma_f32 v90, v106, v3, v90
	s_waitcnt lgkmcnt(7)
	v_mfma_f32_32x32x16_bf16 v[116:131], v[152:155], v[196:199], v[116:131]
	v_fma_f32 v91, v107, v3, v91
	v_cvt_pk_bf16_f32 v36, v76, v77
	v_cvt_pk_bf16_f32 v37, v78, v79
	s_waitcnt lgkmcnt(6)
	v_mfma_f32_32x32x16_bf16 v[116:131], v[156:159], v[200:203], v[116:131]
	v_cvt_pk_bf16_f32 v38, v80, v81
	v_cvt_pk_bf16_f32 v39, v82, v83
	v_cvt_pk_bf16_f32 v72, v84, v85
	s_waitcnt lgkmcnt(5)
	v_mfma_f32_32x32x16_bf16 v[116:131], v[160:163], v[204:207], v[116:131]
	v_cvt_pk_bf16_f32 v73, v86, v87
	v_cvt_pk_bf16_f32 v74, v88, v89
	v_cvt_pk_bf16_f32 v75, v90, v91
	s_cmp_eq_u32 s52, 1
	s_cbranch_scc1 .Lm_yfin1_18
	ds_write_b64 v168, v[36:37] offset:0
	ds_write_b64 v168, v[38:39] offset:16
	ds_write_b64 v168, v[72:73] offset:32
	ds_write_b64 v168, v[74:75] offset:48
	ds_read_b64_tr_b16 v[36:37], v225 offset:0
	ds_read_b64_tr_b16 v[38:39], v225 offset:512
	ds_read_b64_tr_b16 v[72:73], v225 offset:1024
	ds_read_b64_tr_b16 v[74:75], v225 offset:1536
	v_add_u32_e32 v223, s53, v223
	v_add_u32_e32 v208, s54, v208
	v_add_u32_e32 v216, s54, v216
	v_add_u32_e32 v225, s13, v225
	s_waitcnt lgkmcnt(9)
	s_waitcnt lgkmcnt(8)
	ds_read_b128 v[148:151], v223 offset:0
	ds_read_b128 v[152:155], v223 offset:32
	ds_read_b128 v[156:159], v223 offset:64
	ds_read_b128 v[160:163], v223 offset:96
	s_waitcnt lgkmcnt(3)
	v_mfma_f32_32x32x16_bf16 v[132:147], v[148:151], v[176:179], 0
	ds_read_b128 v[148:151], v223 offset:128
	ds_read_b128 v[92:95], v169
	ds_read_b128 v[96:99], v169 offset:1280
	v_sub_f32_e32 v234, v250, v234
	v_sub_f32_e32 v235, v250, v235
	v_sub_f32_e32 v236, v250, v236
	v_sub_f32_e32 v237, v250, v237
	v_sub_f32_e32 v238, v250, v238
	v_sub_f32_e32 v239, v250, v239
	v_sub_f32_e32 v240, v250, v240
	v_sub_f32_e32 v241, v250, v241
	v_sub_f32_e32 v242, v250, v242
	s_waitcnt lgkmcnt(5)
	v_mfma_f32_32x32x16_bf16 v[132:147], v[152:155], v[180:183], v[132:147]
	ds_read_b128 v[152:155], v223 offset:160
	v_sub_f32_e32 v243, v250, v243
	v_sub_f32_e32 v244, v250, v244
	v_sub_f32_e32 v245, v250, v245
	v_sub_f32_e32 v246, v250, v246
	v_sub_f32_e32 v247, v250, v247
	v_sub_f32_e32 v248, v250, v248
	v_sub_f32_e32 v249, v250, v249
	v_exp_f32_e32 v234, v234
	v_exp_f32_e32 v235, v235
	s_waitcnt lgkmcnt(5)
	v_mfma_f32_32x32x16_bf16 v[132:147], v[156:159], v[184:187], v[132:147]
	ds_read_b128 v[156:159], v223 offset:192
	v_exp_f32_e32 v236, v236
	v_exp_f32_e32 v237, v237
	v_exp_f32_e32 v238, v238
	v_exp_f32_e32 v239, v239
	v_exp_f32_e32 v240, v240
	v_exp_f32_e32 v241, v241
	v_exp_f32_e32 v242, v242
	v_exp_f32_e32 v243, v243
	v_exp_f32_e32 v244, v244
	s_waitcnt lgkmcnt(5)
	v_mfma_f32_32x32x16_bf16 v[132:147], v[160:163], v[188:191], v[132:147]
	ds_read_b128 v[160:163], v223 offset:224
	s_waitcnt lgkmcnt(3)
	global_store_dwordx4 v170, v[92:95], s[44:45]
	global_store_dwordx4 v171, v[96:99], s[44:45]
	s_cmp_lg_u32 s50, 0
	s_cselect_b32 s4, s49, 0
	s_cselect_b32 s5, s55, 0
	s_add_u32 s44, s44, s4
	s_addc_u32 s45, s45, s5
	s_waitcnt vmcnt(12)
	v_exp_f32_e32 v245, v245
	v_exp_f32_e32 v246, v246
	v_exp_f32_e32 v247, v247
	v_exp_f32_e32 v248, v248
	v_exp_f32_e32 v249, v249
	v_mul_f32_e32 v116, v116, v234
	v_mul_f32_e32 v117, v117, v235
	v_mul_f32_e32 v118, v118, v236
	v_mul_f32_e32 v119, v119, v237
	v_mfma_f32_32x32x16_bf16 v[132:147], v[148:151], v[192:195], v[132:147]
	ds_write_b128 v166, v[40:43] offset:0
	ds_write_b128 v166, v[44:47] offset:272
	v_mul_f32_e32 v120, v120, v238
	v_mul_f32_e32 v121, v121, v239
	v_mul_f32_e32 v122, v122, v240
	v_mul_f32_e32 v123, v123, v241
	v_mul_f32_e32 v124, v124, v242
	v_mul_f32_e32 v125, v125, v243
	v_mul_f32_e32 v126, v126, v244
	v_mul_f32_e32 v127, v127, v245
	v_mul_f32_e32 v128, v128, v246
	s_waitcnt lgkmcnt(4)
	v_mfma_f32_32x32x16_bf16 v[132:147], v[152:155], v[196:199], v[132:147]
	ds_write_b128 v166, v[48:51] offset:544
	ds_write_b128 v166, v[52:55] offset:816
	v_mul_f32_e32 v129, v129, v247
	v_mul_f32_e32 v130, v130, v248
	v_mul_f32_e32 v131, v131, v249
	v_cndmask_b32_e64 v116, 0, v116, s[64:65]
	v_cndmask_b32_e64 v117, 0, v117, s[66:67]
	v_cndmask_b32_e64 v118, 0, v118, s[68:69]
	v_cndmask_b32_e64 v119, 0, v119, s[70:71]
	v_cndmask_b32_e64 v120, 0, v120, s[72:73]
	v_cndmask_b32_e64 v121, 0, v121, s[74:75]
	s_waitcnt lgkmcnt(5)
	v_mfma_f32_32x32x16_bf16 v[132:147], v[156:159], v[200:203], v[132:147]
	ds_write_b128 v166, v[56:59] offset:1088
	ds_write_b128 v166, v[60:63] offset:1360
	v_cndmask_b32_e64 v122, 0, v122, s[76:77]
	v_cndmask_b32_e64 v123, 0, v123, s[78:79]
	v_cndmask_b32_e64 v124, 0, v124, s[80:81]
	v_cndmask_b32_e64 v125, 0, v125, s[82:83]
	v_cndmask_b32_e64 v126, 0, v126, s[84:85]
	v_cndmask_b32_e64 v127, 0, v127, s[86:87]
	v_cndmask_b32_e64 v128, 0, v128, s[88:89]
	v_cndmask_b32_e64 v129, 0, v129, s[90:91]
	v_cndmask_b32_e64 v130, 0, v130, s[92:93]
	s_waitcnt lgkmcnt(6)
	v_mfma_f32_32x32x16_bf16 v[132:147], v[160:163], v[204:207], v[132:147]
	ds_write_b128 v166, v[64:67] offset:1632
	ds_write_b128 v166, v[68:71] offset:1904
	v_cndmask_b32_e64 v131, 0, v131, s[94:95]
	v_cvt_pk_bf16_f32 v116, v116, v117
	v_cvt_pk_bf16_f32 v117, v118, v119
	v_cvt_pk_bf16_f32 v118, v120, v121
	v_cvt_pk_bf16_f32 v119, v122, v123
	v_cvt_pk_bf16_f32 v120, v124, v125
	v_cvt_pk_bf16_f32 v121, v126, v127
	v_cvt_pk_bf16_f32 v122, v128, v129
	v_cvt_pk_bf16_f32 v123, v130, v131
	global_load_dwordx4 v[40:43], v164, s[38:39] offset:0
	global_load_dwordx4 v[44:47], v164, s[38:39] offset:512
	global_load_dwordx4 v[48:51], v164, s[38:39] offset:1024
	global_load_dwordx4 v[52:55], v164, s[38:39] offset:1536
	global_load_dwordx4 v[56:59], v164, s[38:39] offset:2048
	global_load_dwordx4 v[60:63], v164, s[38:39] offset:2560
	global_load_dwordx4 v[64:67], v164, s[38:39] offset:3072
	global_load_dwordx4 v[68:71], v164, s[38:39] offset:3584
	s_add_u32 s38, s38, s46
	s_addc_u32 s39, s39, s55
	s_waitcnt lgkmcnt(0)
	ds_read_b128 v[234:237], v208 offset:0
	ds_read_b128 v[238:241], v208 offset:32
	ds_read_b128 v[242:245], v208 offset:64
	ds_read_b128 v[246:249], v208 offset:96
	ds_read_b32 v251, v216
	v_mfma_f32_32x32x16_bf16 v[76:91], v[36:39], v[116:119], 0
	v_mfma_f32_32x32x16_bf16 v[76:91], v[72:75], v[120:123], v[76:91]
	s_cmp_eq_u32 s52, 2
	s_cbranch_scc1 .Lm_yfin2_19
	ds_read_b64_tr_b16 v[36:37], v225 offset:0
	ds_read_b64_tr_b16 v[38:39], v225 offset:512
	ds_read_b64_tr_b16 v[72:73], v225 offset:1024
	ds_read_b64_tr_b16 v[74:75], v225 offset:1536
	v_add_u32_e32 v223, s53, v223
	v_add_u32_e32 v208, s54, v208
	v_add_u32_e32 v216, s54, v216
	v_add_u32_e32 v225, s13, v225
	s_waitcnt lgkmcnt(4)
	ds_read_b128 v[148:151], v223 offset:0
	ds_read_b128 v[152:155], v223 offset:32
	ds_read_b128 v[156:159], v223 offset:64
	ds_read_b128 v[160:163], v223 offset:96
	s_waitcnt lgkmcnt(3)
	v_mfma_f32_32x32x16_bf16 v[116:131], v[148:151], v[176:179], 0
	ds_read_b128 v[148:151], v223 offset:128
	v_sub_f32_e32 v2, v250, v251
	v_exp_f32_e32 v2, v2
	s_nop 0
	v_mul_f32_e32 v234, v234, v2
	v_mul_f32_e32 v235, v235, v2
	s_waitcnt lgkmcnt(3)
	v_mfma_f32_32x32x16_bf16 v[116:131], v[152:155], v[180:183], v[116:131]
	ds_read_b128 v[152:155], v223 offset:160
	v_mul_f32_e32 v236, v236, v2
	v_mul_f32_e32 v237, v237, v2
	v_mul_f32_e32 v238, v238, v2
	v_mul_f32_e32 v239, v239, v2
	v_mul_f32_e32 v240, v240, v2
	s_waitcnt lgkmcnt(3)
	v_mfma_f32_32x32x16_bf16 v[116:131], v[156:159], v[184:187], v[116:131]
	ds_read_b128 v[156:159], v223 offset:192
	v_mul_f32_e32 v241, v241, v2
	v_mul_f32_e32 v242, v242, v2
	v_mul_f32_e32 v243, v243, v2
	v_mul_f32_e32 v244, v244, v2
	v_mul_f32_e32 v245, v245, v2
	v_mul_f32_e32 v246, v246, v2
	s_waitcnt lgkmcnt(3)
	v_mfma_f32_32x32x16_bf16 v[116:131], v[160:163], v[188:191], v[116:131]
	ds_read_b128 v[160:163], v223 offset:224
	v_mul_f32_e32 v247, v247, v2
	v_mul_f32_e32 v248, v248, v2
	v_mul_f32_e32 v249, v249, v2
	v_mul_f32_e32 v132, v132, v234
	v_mul_f32_e32 v133, v133, v235
	s_waitcnt lgkmcnt(3)
	v_mfma_f32_32x32x16_bf16 v[116:131], v[148:151], v[192:195], v[116:131]
	v_mul_f32_e32 v134, v134, v236
	v_mul_f32_e32 v135, v135, v237
	v_mul_f32_e32 v136, v136, v238
	v_mul_f32_e32 v137, v137, v239
	v_mul_f32_e32 v138, v138, v240
	s_waitcnt lgkmcnt(2)
	v_mfma_f32_32x32x16_bf16 v[116:131], v[152:155], v[196:199], v[116:131]
	v_mul_f32_e32 v139, v139, v241
	v_mul_f32_e32 v140, v140, v242
	v_mul_f32_e32 v141, v141, v243
	v_mul_f32_e32 v142, v142, v244
	v_mul_f32_e32 v143, v143, v245
	v_mul_f32_e32 v144, v144, v246
	s_waitcnt lgkmcnt(1)
	v_mfma_f32_32x32x16_bf16 v[116:131], v[156:159], v[200:203], v[116:131]
	v_mul_f32_e32 v145, v145, v247
	v_mul_f32_e32 v146, v146, v248
	v_mul_f32_e32 v147, v147, v249
	v_cvt_pk_bf16_f32 v132, v132, v133
	v_cvt_pk_bf16_f32 v133, v134, v135
	s_waitcnt lgkmcnt(0)
	v_mfma_f32_32x32x16_bf16 v[116:131], v[160:163], v[204:207], v[116:131]
	v_cvt_pk_bf16_f32 v134, v136, v137
	v_cvt_pk_bf16_f32 v135, v138, v139
	v_cvt_pk_bf16_f32 v136, v140, v141
	v_cvt_pk_bf16_f32 v137, v142, v143
	v_cvt_pk_bf16_f32 v138, v144, v145
	v_cvt_pk_bf16_f32 v139, v146, v147
	ds_read_b128 v[234:237], v208 offset:0
	ds_read_b128 v[238:241], v208 offset:32
	ds_read_b128 v[242:245], v208 offset:64
	ds_read_b128 v[246:249], v208 offset:96
	ds_read_b32 v251, v216
	v_mfma_f32_32x32x16_bf16 v[76:91], v[36:39], v[132:135], v[76:91]
	v_mfma_f32_32x32x16_bf16 v[76:91], v[72:75], v[136:139], v[76:91]
	s_cmp_eq_u32 s52, 3
	s_cbranch_scc1 .Lm_yfin3_20
	ds_read_b64_tr_b16 v[36:37], v225 offset:0
	ds_read_b64_tr_b16 v[38:39], v225 offset:512
	ds_read_b64_tr_b16 v[72:73], v225 offset:1024
	ds_read_b64_tr_b16 v[74:75], v225 offset:1536
	v_add_u32_e32 v223, s53, v223
	v_add_u32_e32 v208, s54, v208
	v_add_u32_e32 v216, s54, v216
	v_add_u32_e32 v225, s13, v225
	s_waitcnt lgkmcnt(4)
	ds_read_b128 v[148:151], v223 offset:0
	ds_read_b128 v[152:155], v223 offset:32
	ds_read_b128 v[156:159], v223 offset:64
	ds_read_b128 v[160:163], v223 offset:96
	s_waitcnt lgkmcnt(3)
	v_mfma_f32_32x32x16_bf16 v[132:147], v[148:151], v[176:179], 0
	ds_read_b128 v[148:151], v223 offset:128
	v_sub_f32_e32 v2, v250, v251
	v_exp_f32_e32 v2, v2
	s_nop 0
	v_mul_f32_e32 v234, v234, v2
	v_mul_f32_e32 v235, v235, v2
	s_waitcnt lgkmcnt(3)
	v_mfma_f32_32x32x16_bf16 v[132:147], v[152:155], v[180:183], v[132:147]
	ds_read_b128 v[152:155], v223 offset:160
	v_mul_f32_e32 v236, v236, v2
	v_mul_f32_e32 v237, v237, v2
	v_mul_f32_e32 v238, v238, v2
	v_mul_f32_e32 v239, v239, v2
	v_mul_f32_e32 v240, v240, v2
	s_waitcnt lgkmcnt(3)
	v_mfma_f32_32x32x16_bf16 v[132:147], v[156:159], v[184:187], v[132:147]
	ds_read_b128 v[156:159], v223 offset:192
	v_mul_f32_e32 v241, v241, v2
	v_mul_f32_e32 v242, v242, v2
	v_mul_f32_e32 v243, v243, v2
	v_mul_f32_e32 v244, v244, v2
	v_mul_f32_e32 v245, v245, v2
	v_mul_f32_e32 v246, v246, v2
	s_waitcnt lgkmcnt(3)
	v_mfma_f32_32x32x16_bf16 v[132:147], v[160:163], v[188:191], v[132:147]
	ds_read_b128 v[160:163], v223 offset:224
	v_mul_f32_e32 v247, v247, v2
	v_mul_f32_e32 v248, v248, v2
	v_mul_f32_e32 v249, v249, v2
	v_mul_f32_e32 v116, v116, v234
	v_mul_f32_e32 v117, v117, v235
	s_waitcnt lgkmcnt(3)
	v_mfma_f32_32x32x16_bf16 v[132:147], v[148:151], v[192:195], v[132:147]
	v_mul_f32_e32 v118, v118, v236
	v_mul_f32_e32 v119, v119, v237
	v_mul_f32_e32 v120, v120, v238
	v_mul_f32_e32 v121, v121, v239
	v_mul_f32_e32 v122, v122, v240
	s_waitcnt lgkmcnt(2)
	v_mfma_f32_32x32x16_bf16 v[132:147], v[152:155], v[196:199], v[132:147]
	v_mul_f32_e32 v123, v123, v241
	v_mul_f32_e32 v124, v124, v242
	v_mul_f32_e32 v125, v125, v243
	v_mul_f32_e32 v126, v126, v244
	v_mul_f32_e32 v127, v127, v245
	v_mul_f32_e32 v128, v128, v246
	s_waitcnt lgkmcnt(1)
	v_mfma_f32_32x32x16_bf16 v[132:147], v[156:159], v[200:203], v[132:147]
	v_mul_f32_e32 v129, v129, v247
	v_mul_f32_e32 v130, v130, v248
	v_mul_f32_e32 v131, v131, v249
	v_cvt_pk_bf16_f32 v116, v116, v117
	v_cvt_pk_bf16_f32 v117, v118, v119
	s_waitcnt lgkmcnt(0)
	v_mfma_f32_32x32x16_bf16 v[132:147], v[160:163], v[204:207], v[132:147]
	v_cvt_pk_bf16_f32 v118, v120, v121
	v_cvt_pk_bf16_f32 v119, v122, v123
	v_cvt_pk_bf16_f32 v120, v124, v125
	v_cvt_pk_bf16_f32 v121, v126, v127
	v_cvt_pk_bf16_f32 v122, v128, v129
	v_cvt_pk_bf16_f32 v123, v130, v131
	ds_read_b128 v[234:237], v208 offset:0
	ds_read_b128 v[238:241], v208 offset:32
	ds_read_b128 v[242:245], v208 offset:64
	ds_read_b128 v[246:249], v208 offset:96
	ds_read_b32 v251, v216
	v_mfma_f32_32x32x16_bf16 v[76:91], v[36:39], v[116:119], v[76:91]
	v_mfma_f32_32x32x16_bf16 v[76:91], v[72:75], v[120:123], v[76:91]
	ds_read_b64_tr_b16 v[36:37], v225 offset:0
	ds_read_b64_tr_b16 v[38:39], v225 offset:512
	ds_read_b64_tr_b16 v[72:73], v225 offset:1024
	ds_read_b64_tr_b16 v[74:75], v225 offset:1536
	s_waitcnt lgkmcnt(4)
	ds_read_b128 v[148:151], v210 offset:0
	ds_read_b128 v[152:155], v210 offset:32
	ds_read_b128 v[156:159], v210 offset:64
	ds_read_b128 v[160:163], v210 offset:96
	s_waitcnt lgkmcnt(3)
	v_mfma_f32_32x32x16_bf16 v[92:107], v[148:151], v[176:179], 0
	ds_read_b128 v[148:151], v210 offset:128
	v_sub_f32_e32 v2, v250, v251
	v_exp_f32_e32 v2, v2
	s_nop 0
	v_mul_f32_e32 v234, v234, v2
	v_mul_f32_e32 v235, v235, v2
	s_waitcnt lgkmcnt(3)
	v_mfma_f32_32x32x16_bf16 v[92:107], v[152:155], v[180:183], v[92:107]
	ds_read_b128 v[152:155], v210 offset:160
	v_mul_f32_e32 v236, v236, v2
	v_mul_f32_e32 v237, v237, v2
	v_mul_f32_e32 v238, v238, v2
	v_mul_f32_e32 v239, v239, v2
	v_mul_f32_e32 v240, v240, v2
	s_waitcnt lgkmcnt(3)
	v_mfma_f32_32x32x16_bf16 v[92:107], v[156:159], v[184:187], v[92:107]
	ds_read_b128 v[156:159], v210 offset:192
	v_mul_f32_e32 v241, v241, v2
	v_mul_f32_e32 v242, v242, v2
	v_mul_f32_e32 v243, v243, v2
	v_mul_f32_e32 v244, v244, v2
	v_mul_f32_e32 v245, v245, v2
	v_mul_f32_e32 v246, v246, v2
	s_waitcnt lgkmcnt(3)
	v_mfma_f32_32x32x16_bf16 v[92:107], v[160:163], v[188:191], v[92:107]
	ds_read_b128 v[160:163], v210 offset:224
	v_mul_f32_e32 v247, v247, v2
	v_mul_f32_e32 v248, v248, v2
	v_mul_f32_e32 v249, v249, v2
	v_mul_f32_e32 v132, v132, v234
	v_mul_f32_e32 v133, v133, v235
	s_waitcnt lgkmcnt(3)
	v_mfma_f32_32x32x16_bf16 v[92:107], v[148:151], v[192:195], v[92:107]
	v_mul_f32_e32 v134, v134, v236
	v_mul_f32_e32 v135, v135, v237
	v_mul_f32_e32 v136, v136, v238
	v_mul_f32_e32 v137, v137, v239
	v_mul_f32_e32 v138, v138, v240
	s_waitcnt lgkmcnt(2)
	v_mfma_f32_32x32x16_bf16 v[92:107], v[152:155], v[196:199], v[92:107]
	v_mul_f32_e32 v139, v139, v241
	v_mul_f32_e32 v140, v140, v242
	v_mul_f32_e32 v141, v141, v243
	v_mul_f32_e32 v142, v142, v244
	v_mul_f32_e32 v143, v143, v245
	v_mul_f32_e32 v144, v144, v246
	s_waitcnt lgkmcnt(1)
	v_mfma_f32_32x32x16_bf16 v[92:107], v[156:159], v[200:203], v[92:107]
	v_mul_f32_e32 v145, v145, v247
	v_mul_f32_e32 v146, v146, v248
	v_mul_f32_e32 v147, v147, v249
	v_cvt_pk_bf16_f32 v132, v132, v133
	v_cvt_pk_bf16_f32 v133, v134, v135
	s_waitcnt lgkmcnt(0)
	v_mfma_f32_32x32x16_bf16 v[92:107], v[160:163], v[204:207], v[92:107]
	v_cvt_pk_bf16_f32 v134, v136, v137
	v_cvt_pk_bf16_f32 v135, v138, v139
	v_cvt_pk_bf16_f32 v136, v140, v141
	v_cvt_pk_bf16_f32 v137, v142, v143
	v_cvt_pk_bf16_f32 v138, v144, v145
	v_cvt_pk_bf16_f32 v139, v146, v147
	v_mfma_f32_32x32x16_bf16 v[76:91], v[36:39], v[132:135], v[76:91]
	v_mfma_f32_32x32x16_bf16 v[76:91], v[72:75], v[136:139], v[76:91]
	s_branch .Lm_ydone_21
.Lm_yfin1_18:
	ds_write_b64 v168, v[36:37] offset:0
	ds_write_b64 v168, v[38:39] offset:16
	ds_write_b64 v168, v[72:73] offset:32
	ds_write_b64 v168, v[74:75] offset:48
	s_waitcnt lgkmcnt(0)
	ds_read_b128 v[92:95], v169
	ds_read_b128 v[96:99], v169 offset:1280
	s_waitcnt lgkmcnt(0)
	global_store_dwordx4 v170, v[92:95], s[44:45]
	global_store_dwordx4 v171, v[96:99], s[44:45]
	s_cmp_lg_u32 s50, 0
	s_cselect_b32 s4, s49, 0
	s_cselect_b32 s5, s55, 0
	s_add_u32 s44, s44, s4
	s_addc_u32 s45, s45, s5
	s_waitcnt vmcnt(16)
	ds_write_b128 v166, v[40:43] offset:0
	ds_write_b128 v166, v[44:47] offset:272
	ds_write_b128 v166, v[48:51] offset:544
	ds_write_b128 v166, v[52:55] offset:816
	ds_write_b128 v166, v[56:59] offset:1088
	ds_write_b128 v166, v[60:63] offset:1360
	ds_write_b128 v166, v[64:67] offset:1632
	ds_write_b128 v166, v[68:71] offset:1904
	global_load_dwordx4 v[40:43], v164, s[38:39] offset:0
	global_load_dwordx4 v[44:47], v164, s[38:39] offset:512
	global_load_dwordx4 v[48:51], v164, s[38:39] offset:1024
	global_load_dwordx4 v[52:55], v164, s[38:39] offset:1536
	global_load_dwordx4 v[56:59], v164, s[38:39] offset:2048
	global_load_dwordx4 v[60:63], v164, s[38:39] offset:2560
	global_load_dwordx4 v[64:67], v164, s[38:39] offset:3072
	global_load_dwordx4 v[68:71], v164, s[38:39] offset:3584
	s_add_u32 s38, s38, s46
	s_addc_u32 s39, s39, s55
	s_waitcnt lgkmcnt(0)
	ds_read_b64_tr_b16 v[36:37], v225 offset:0
	ds_read_b64_tr_b16 v[38:39], v225 offset:512
	ds_read_b64_tr_b16 v[72:73], v225 offset:1024
	ds_read_b64_tr_b16 v[74:75], v225 offset:1536
	ds_read_b128 v[148:151], v210 offset:0
	ds_read_b128 v[152:155], v210 offset:32
	ds_read_b128 v[156:159], v210 offset:64
	ds_read_b128 v[160:163], v210 offset:96
	s_waitcnt lgkmcnt(3)
	v_mfma_f32_32x32x16_bf16 v[92:107], v[148:151], v[176:179], 0
	ds_read_b128 v[148:151], v210 offset:128
	v_sub_f32_e32 v234, v250, v234
	v_sub_f32_e32 v235, v250, v235
	v_sub_f32_e32 v236, v250, v236
	v_sub_f32_e32 v237, v250, v237
	v_sub_f32_e32 v238, v250, v238
	v_sub_f32_e32 v239, v250, v239
	v_sub_f32_e32 v240, v250, v240
	v_sub_f32_e32 v241, v250, v241
	v_sub_f32_e32 v242, v250, v242
	s_waitcnt lgkmcnt(3)
	v_mfma_f32_32x32x16_bf16 v[92:107], v[152:155], v[180:183], v[92:107]
	ds_read_b128 v[152:155], v210 offset:160
	v_sub_f32_e32 v243, v250, v243
	v_sub_f32_e32 v244, v250, v244
	v_sub_f32_e32 v245, v250, v245
	v_sub_f32_e32 v246, v250, v246
	v_sub_f32_e32 v247, v250, v247
	v_sub_f32_e32 v248, v250, v248
	v_sub_f32_e32 v249, v250, v249
	v_exp_f32_e32 v234, v234
	v_exp_f32_e32 v235, v235
	s_waitcnt lgkmcnt(3)
	v_mfma_f32_32x32x16_bf16 v[92:107], v[156:159], v[184:187], v[92:107]
	ds_read_b128 v[156:159], v210 offset:192
	v_exp_f32_e32 v236, v236
	v_exp_f32_e32 v237, v237
	v_exp_f32_e32 v238, v238
	v_exp_f32_e32 v239, v239
	v_exp_f32_e32 v240, v240
	v_exp_f32_e32 v241, v241
	v_exp_f32_e32 v242, v242
	v_exp_f32_e32 v243, v243
	v_exp_f32_e32 v244, v244
	s_waitcnt lgkmcnt(3)
	v_mfma_f32_32x32x16_bf16 v[92:107], v[160:163], v[188:191], v[92:107]
	ds_read_b128 v[160:163], v210 offset:224
	v_exp_f32_e32 v245, v245
	v_exp_f32_e32 v246, v246
	v_exp_f32_e32 v247, v247
	v_exp_f32_e32 v248, v248
	v_exp_f32_e32 v249, v249
	v_mul_f32_e32 v116, v116, v234
	v_mul_f32_e32 v117, v117, v235
	v_mul_f32_e32 v118, v118, v236
	v_mul_f32_e32 v119, v119, v237
	s_waitcnt lgkmcnt(3)
	v_mfma_f32_32x32x16_bf16 v[92:107], v[148:151], v[192:195], v[92:107]
	v_mul_f32_e32 v120, v120, v238
	v_mul_f32_e32 v121, v121, v239
	v_mul_f32_e32 v122, v122, v240
	v_mul_f32_e32 v123, v123, v241
	v_mul_f32_e32 v124, v124, v242
	v_mul_f32_e32 v125, v125, v243
	v_mul_f32_e32 v126, v126, v244
	v_mul_f32_e32 v127, v127, v245
	v_mul_f32_e32 v128, v128, v246
	s_waitcnt lgkmcnt(2)
	v_mfma_f32_32x32x16_bf16 v[92:107], v[152:155], v[196:199], v[92:107]
	v_mul_f32_e32 v129, v129, v247
	v_mul_f32_e32 v130, v130, v248
	v_mul_f32_e32 v131, v131, v249
	v_cndmask_b32_e64 v116, 0, v116, s[64:65]
	v_cndmask_b32_e64 v117, 0, v117, s[66:67]
	v_cndmask_b32_e64 v118, 0, v118, s[68:69]
	v_cndmask_b32_e64 v119, 0, v119, s[70:71]
	v_cndmask_b32_e64 v120, 0, v120, s[72:73]
	v_cndmask_b32_e64 v121, 0, v121, s[74:75]
	s_waitcnt lgkmcnt(1)
	v_mfma_f32_32x32x16_bf16 v[92:107], v[156:159], v[200:203], v[92:107]
	v_cndmask_b32_e64 v122, 0, v122, s[76:77]
	v_cndmask_b32_e64 v123, 0, v123, s[78:79]
	v_cndmask_b32_e64 v124, 0, v124, s[80:81]
	v_cndmask_b32_e64 v125, 0, v125, s[82:83]
	v_cndmask_b32_e64 v126, 0, v126, s[84:85]
	v_cndmask_b32_e64 v127, 0, v127, s[86:87]
	v_cndmask_b32_e64 v128, 0, v128, s[88:89]
	v_cndmask_b32_e64 v129, 0, v129, s[90:91]
	v_cndmask_b32_e64 v130, 0, v130, s[92:93]
	s_waitcnt lgkmcnt(0)
	v_mfma_f32_32x32x16_bf16 v[92:107], v[160:163], v[204:207], v[92:107]
	v_cndmask_b32_e64 v131, 0, v131, s[94:95]
	v_cvt_pk_bf16_f32 v116, v116, v117
	v_cvt_pk_bf16_f32 v117, v118, v119
	v_cvt_pk_bf16_f32 v118, v120, v121
	v_cvt_pk_bf16_f32 v119, v122, v123
	v_cvt_pk_bf16_f32 v120, v124, v125
	v_cvt_pk_bf16_f32 v121, v126, v127
	v_cvt_pk_bf16_f32 v122, v128, v129
	v_cvt_pk_bf16_f32 v123, v130, v131
	v_mfma_f32_32x32x16_bf16 v[76:91], v[36:39], v[116:119], 0
	v_mfma_f32_32x32x16_bf16 v[76:91], v[72:75], v[120:123], v[76:91]
	s_waitcnt vmcnt(10)
	v_mul_f32_e32 v132, s62, v146
	v_mul_f32_e32 v133, s62, v147
	v_add_f32_e32 v134, v132, v133
	v_and_b32_e32 v140, 63, v175
	v_lshrrev_b32_e32 v142, 4, v140
	v_add_f32_dpp v134, v134, v134 row_shr:1 row_mask:0xf bank_mask:0xf bound_ctrl:0
	s_nop 1
	v_add_f32_dpp v134, v134, v134 row_shr:2 row_mask:0xf bank_mask:0xf bound_ctrl:0
	s_nop 1
	v_add_f32_dpp v134, v134, v134 row_shr:4 row_mask:0xf bank_mask:0xf bound_ctrl:0
	s_nop 1
	v_add_f32_dpp v134, v134, v134 row_shr:8 row_mask:0xf bank_mask:0xf bound_ctrl:0
	s_nop 1
	v_add_f32_dpp v134, v134, v134 row_bcast:15 row_mask:0xa bank_mask:0xf
	s_nop 1
	v_add_f32_dpp v134, v134, v134 row_bcast:31 row_mask:0xc bank_mask:0xf
	v_lshlrev_b32_e32 v140, 3, v140
	v_lshlrev_b32_e32 v142, 7, v142
	v_readlane_b32 s97, v134, 63
	v_sub_f32_e32 v138, v134, v133
	v_mov_b32_e32 v139, v134
	v_add_u32_e32 v143, 0x1d800, v140
	v_add_u32_e32 v143, s20, v143
	s_cmp_eq_u32 s51, 0
	s_cbranch_scc1 .Lm_scanf_22
	v_sub_f32_e32 v138, s97, v138
	v_sub_f32_e32 v139, s97, v139
	v_fma_f32 v138, v146, s62, v138
	v_fma_f32 v139, v147, s62, v139
.Lm_scanf_22:
	s_add_u32 s4, s17, 0x22c00
	v_mov_b32_e32 v135, s97
	v_add_u32_e32 v140, s4, v140
	s_add_u32 s5, s4, s21
	v_add_u32_e32 v142, s5, v142
	s_add_u32 s4, s4, 0x400
	v_mov_b32_e32 v141, s4
	v_mul_f32_e32 v138, 0x3fb8aa3b, v138
	v_mul_f32_e32 v139, 0x3fb8aa3b, v139
	v_mul_f32_e32 v135, 0x3fb8aa3b, v135
	ds_write_b64 v140, v[138:139]
	ds_write_b64 v140, v[146:147] offset:512
	ds_write_b32 v141, v135
	v_mov_b32_e32 v140, v143
	s_waitcnt lgkmcnt(0)
	ds_read_b32 v143, v142
	s_waitcnt lgkmcnt(0)
	v_sub_f32_e32 v144, v143, v138
	v_sub_f32_e32 v145, v143, v139
	v_exp_f32_e32 v144, v144
	v_exp_f32_e32 v145, v145
	s_nop 0
	ds_write_b64 v140, v[144:145]
	s_waitcnt lgkmcnt(0)
	v_and_b32_e32 v132, 63, v175
	v_lshlrev_b32_e32 v132, 9, v132
	global_load_dword v146, v132, s[42:43]
	global_load_dword v147, v132, s[42:43] offset:256
	s_add_u32 s42, s42, s48
	s_addc_u32 s43, s43, s55
	s_branch .Lm_ydone_21
.Lm_yfin2_19:
	ds_read_b64_tr_b16 v[36:37], v225 offset:0
	ds_read_b64_tr_b16 v[38:39], v225 offset:512
	ds_read_b64_tr_b16 v[72:73], v225 offset:1024
	ds_read_b64_tr_b16 v[74:75], v225 offset:1536
	s_waitcnt lgkmcnt(4)
	ds_read_b128 v[148:151], v210 offset:0
	ds_read_b128 v[152:155], v210 offset:32
	ds_read_b128 v[156:159], v210 offset:64
	ds_read_b128 v[160:163], v210 offset:96
	s_waitcnt lgkmcnt(3)
	v_mfma_f32_32x32x16_bf16 v[92:107], v[148:151], v[176:179], 0
	ds_read_b128 v[148:151], v210 offset:128
	v_sub_f32_e32 v2, v250, v251
	v_exp_f32_e32 v2, v2
	s_nop 0
	v_mul_f32_e32 v234, v234, v2
	v_mul_f32_e32 v235, v235, v2
	s_waitcnt lgkmcnt(3)
	v_mfma_f32_32x32x16_bf16 v[92:107], v[152:155], v[180:183], v[92:107]
	ds_read_b128 v[152:155], v210 offset:160
	v_mul_f32_e32 v236, v236, v2
	v_mul_f32_e32 v237, v237, v2
	v_mul_f32_e32 v238, v238, v2
	v_mul_f32_e32 v239, v239, v2
	v_mul_f32_e32 v240, v240, v2
	s_waitcnt lgkmcnt(3)
	v_mfma_f32_32x32x16_bf16 v[92:107], v[156:159], v[184:187], v[92:107]
	ds_read_b128 v[156:159], v210 offset:192
	v_mul_f32_e32 v241, v241, v2
	v_mul_f32_e32 v242, v242, v2
	v_mul_f32_e32 v243, v243, v2
	v_mul_f32_e32 v244, v244, v2
	v_mul_f32_e32 v245, v245, v2
	v_mul_f32_e32 v246, v246, v2
	s_waitcnt lgkmcnt(3)
	v_mfma_f32_32x32x16_bf16 v[92:107], v[160:163], v[188:191], v[92:107]
	ds_read_b128 v[160:163], v210 offset:224
	v_mul_f32_e32 v247, v247, v2
	v_mul_f32_e32 v248, v248, v2
	v_mul_f32_e32 v249, v249, v2
	v_mul_f32_e32 v132, v132, v234
	v_mul_f32_e32 v133, v133, v235
	s_waitcnt lgkmcnt(3)
	v_mfma_f32_32x32x16_bf16 v[92:107], v[148:151], v[192:195], v[92:107]
	v_mul_f32_e32 v134, v134, v236
	v_mul_f32_e32 v135, v135, v237
	v_mul_f32_e32 v136, v136, v238
	v_mul_f32_e32 v137, v137, v239
	v_mul_f32_e32 v138, v138, v240
	s_waitcnt lgkmcnt(2)
	v_mfma_f32_32x32x16_bf16 v[92:107], v[152:155], v[196:199], v[92:107]
	v_mul_f32_e32 v139, v139, v241
	v_mul_f32_e32 v140, v140, v242
	v_mul_f32_e32 v141, v141, v243
	v_mul_f32_e32 v142, v142, v244
	v_mul_f32_e32 v143, v143, v245
	v_mul_f32_e32 v144, v144, v246
	s_waitcnt lgkmcnt(1)
	v_mfma_f32_32x32x16_bf16 v[92:107], v[156:159], v[200:203], v[92:107]
	v_mul_f32_e32 v145, v145, v247
	v_mul_f32_e32 v146, v146, v248
	v_mul_f32_e32 v147, v147, v249
	v_cvt_pk_bf16_f32 v132, v132, v133
	v_cvt_pk_bf16_f32 v133, v134, v135
	s_waitcnt lgkmcnt(0)
	v_mfma_f32_32x32x16_bf16 v[92:107], v[160:163], v[204:207], v[92:107]
	v_cvt_pk_bf16_f32 v134, v136, v137
	v_cvt_pk_bf16_f32 v135, v138, v139
	v_cvt_pk_bf16_f32 v136, v140, v141
	v_cvt_pk_bf16_f32 v137, v142, v143
	v_cvt_pk_bf16_f32 v138, v144, v145
	v_cvt_pk_bf16_f32 v139, v146, v147
	v_mfma_f32_32x32x16_bf16 v[76:91], v[36:39], v[132:135], v[76:91]
	v_mfma_f32_32x32x16_bf16 v[76:91], v[72:75], v[136:139], v[76:91]
	s_branch .Lm_ydone_21
.Lm_yfin3_20:
	ds_read_b64_tr_b16 v[36:37], v225 offset:0
	ds_read_b64_tr_b16 v[38:39], v225 offset:512
	ds_read_b64_tr_b16 v[72:73], v225 offset:1024
	ds_read_b64_tr_b16 v[74:75], v225 offset:1536
	s_waitcnt lgkmcnt(4)
	ds_read_b128 v[148:151], v210 offset:0
	ds_read_b128 v[152:155], v210 offset:32
	ds_read_b128 v[156:159], v210 offset:64
	ds_read_b128 v[160:163], v210 offset:96
	s_waitcnt lgkmcnt(3)
	v_mfma_f32_32x32x16_bf16 v[92:107], v[148:151], v[176:179], 0
	ds_read_b128 v[148:151], v210 offset:128
	v_sub_f32_e32 v2, v250, v251
	v_exp_f32_e32 v2, v2
	s_nop 0
	v_mul_f32_e32 v234, v234, v2
	v_mul_f32_e32 v235, v235, v2
	s_waitcnt lgkmcnt(3)
	v_mfma_f32_32x32x16_bf16 v[92:107], v[152:155], v[180:183], v[92:107]
	ds_read_b128 v[152:155], v210 offset:160
	v_mul_f32_e32 v236, v236, v2
	v_mul_f32_e32 v237, v237, v2
	v_mul_f32_e32 v238, v238, v2
	v_mul_f32_e32 v239, v239, v2
	v_mul_f32_e32 v240, v240, v2
	s_waitcnt lgkmcnt(3)
	v_mfma_f32_32x32x16_bf16 v[92:107], v[156:159], v[184:187], v[92:107]
	ds_read_b128 v[156:159], v210 offset:192
	v_mul_f32_e32 v241, v241, v2
	v_mul_f32_e32 v242, v242, v2
	v_mul_f32_e32 v243, v243, v2
	v_mul_f32_e32 v244, v244, v2
	v_mul_f32_e32 v245, v245, v2
	v_mul_f32_e32 v246, v246, v2
	s_waitcnt lgkmcnt(3)
	v_mfma_f32_32x32x16_bf16 v[92:107], v[160:163], v[188:191], v[92:107]
	ds_read_b128 v[160:163], v210 offset:224
	v_mul_f32_e32 v247, v247, v2
	v_mul_f32_e32 v248, v248, v2
	v_mul_f32_e32 v249, v249, v2
	v_mul_f32_e32 v116, v116, v234
	v_mul_f32_e32 v117, v117, v235
	s_waitcnt lgkmcnt(3)
	v_mfma_f32_32x32x16_bf16 v[92:107], v[148:151], v[192:195], v[92:107]
	v_mul_f32_e32 v118, v118, v236
	v_mul_f32_e32 v119, v119, v237
	v_mul_f32_e32 v120, v120, v238
	v_mul_f32_e32 v121, v121, v239
	v_mul_f32_e32 v122, v122, v240
	s_waitcnt lgkmcnt(2)
	v_mfma_f32_32x32x16_bf16 v[92:107], v[152:155], v[196:199], v[92:107]
	v_mul_f32_e32 v123, v123, v241
	v_mul_f32_e32 v124, v124, v242
	v_mul_f32_e32 v125, v125, v243
	v_mul_f32_e32 v126, v126, v244
	v_mul_f32_e32 v127, v127, v245
	v_mul_f32_e32 v128, v128, v246
	s_waitcnt lgkmcnt(1)
	v_mfma_f32_32x32x16_bf16 v[92:107], v[156:159], v[200:203], v[92:107]
	v_mul_f32_e32 v129, v129, v247
	v_mul_f32_e32 v130, v130, v248
	v_mul_f32_e32 v131, v131, v249
	v_cvt_pk_bf16_f32 v116, v116, v117
	v_cvt_pk_bf16_f32 v117, v118, v119
	s_waitcnt lgkmcnt(0)
	v_mfma_f32_32x32x16_bf16 v[92:107], v[160:163], v[204:207], v[92:107]
	v_cvt_pk_bf16_f32 v118, v120, v121
	v_cvt_pk_bf16_f32 v119, v122, v123
	v_cvt_pk_bf16_f32 v120, v124, v125
	v_cvt_pk_bf16_f32 v121, v126, v127
	v_cvt_pk_bf16_f32 v122, v128, v129
	v_cvt_pk_bf16_f32 v123, v130, v131
	v_mfma_f32_32x32x16_bf16 v[76:91], v[36:39], v[116:119], v[76:91]
	v_mfma_f32_32x32x16_bf16 v[76:91], v[72:75], v[120:123], v[76:91]
.Lm_ydone_21:
	s_waitcnt lgkmcnt(0)
	v_exp_f32_e32 v3, v250
	s_branch .Lm_stepdone_14
.Lm_hi_13:
	v_add_u32_e32 v2, s14, v173
	ds_read_b32 v1, v2
	ds_read_b64_tr_b16 v[116:117], v193 offset:0
	ds_read_b64_tr_b16 v[118:119], v193 offset:1088
	ds_read_b64_tr_b16 v[120:121], v192 offset:0
	ds_read_b64_tr_b16 v[122:123], v192 offset:256
	ds_read_b64_tr_b16 v[124:125], v193 offset:4352
	ds_read_b64_tr_b16 v[126:127], v193 offset:5440
	ds_read_b64_tr_b16 v[128:129], v192 offset:1024
	ds_read_b64_tr_b16 v[130:131], v192 offset:1280
	ds_read_b64_tr_b16 v[132:133], v193 offset:8704
	ds_read_b64_tr_b16 v[134:135], v193 offset:9792
	ds_read_b64_tr_b16 v[136:137], v192 offset:2048
	ds_read_b64_tr_b16 v[138:139], v192 offset:2304
	s_waitcnt lgkmcnt(12)
	v_exp_f32_e32 v1, v1
	s_nop 0
	v_mul_f32_e32 v176, v176, v1
	v_mul_f32_e32 v177, v177, v1
	v_mul_f32_e32 v178, v178, v1
	v_mul_f32_e32 v179, v179, v1
	v_mul_f32_e32 v180, v180, v1
	v_mul_f32_e32 v181, v181, v1
	v_mul_f32_e32 v182, v182, v1
	v_mul_f32_e32 v183, v183, v1
	v_mul_f32_e32 v184, v184, v1
	v_mul_f32_e32 v185, v185, v1
	v_mul_f32_e32 v186, v186, v1
	v_mul_f32_e32 v187, v187, v1
	v_mul_f32_e32 v188, v188, v1
	v_mul_f32_e32 v189, v189, v1
	v_mul_f32_e32 v190, v190, v1
	v_mul_f32_e32 v191, v191, v1
	s_nop 1
	s_waitcnt lgkmcnt(8)
	v_mfma_f32_32x32x16_bf16 v[176:191], v[116:119], v[120:123], v[176:191]
	ds_read_b64_tr_b16 v[116:117], v193 offset:13056
	ds_read_b64_tr_b16 v[118:119], v193 offset:14144
	ds_read_b64_tr_b16 v[120:121], v192 offset:3072
	ds_read_b64_tr_b16 v[122:123], v192 offset:3328
	s_waitcnt lgkmcnt(8)
	v_mfma_f32_32x32x16_bf16 v[176:191], v[124:127], v[128:131], v[176:191]
	ds_read_b64_tr_b16 v[124:125], v193 offset:17408
	ds_read_b64_tr_b16 v[126:127], v193 offset:18496
	ds_read_b64_tr_b16 v[128:129], v192 offset:4096
	ds_read_b64_tr_b16 v[130:131], v192 offset:4352
	s_waitcnt lgkmcnt(8)
	v_mfma_f32_32x32x16_bf16 v[176:191], v[132:135], v[136:139], v[176:191]
	ds_read_b64_tr_b16 v[132:133], v193 offset:21760
	ds_read_b64_tr_b16 v[134:135], v193 offset:22848
	ds_read_b64_tr_b16 v[136:137], v192 offset:5120
	ds_read_b64_tr_b16 v[138:139], v192 offset:5376
	s_waitcnt lgkmcnt(8)
	v_mfma_f32_32x32x16_bf16 v[176:191], v[116:119], v[120:123], v[176:191]
	ds_read_b64_tr_b16 v[116:117], v193 offset:26112
	ds_read_b64_tr_b16 v[118:119], v193 offset:27200
	ds_read_b64_tr_b16 v[120:121], v192 offset:6144
	ds_read_b64_tr_b16 v[122:123], v192 offset:6400
	s_waitcnt lgkmcnt(8)
	v_mfma_f32_32x32x16_bf16 v[176:191], v[124:127], v[128:131], v[176:191]
	ds_read_b64_tr_b16 v[124:125], v193 offset:30464
	ds_read_b64_tr_b16 v[126:127], v193 offset:31552
	ds_read_b64_tr_b16 v[128:129], v192 offset:7168
	ds_read_b64_tr_b16 v[130:131], v192 offset:7424
	s_waitcnt lgkmcnt(8)
	v_mfma_f32_32x32x16_bf16 v[176:191], v[132:135], v[136:139], v[176:191]
	s_waitcnt lgkmcnt(4)
	v_mfma_f32_32x32x16_bf16 v[176:191], v[116:119], v[120:123], v[176:191]
	s_waitcnt lgkmcnt(0)
	v_mfma_f32_32x32x16_bf16 v[176:191], v[124:127], v[128:131], v[176:191]
	s_nop 7
	s_nop 3
	v_cvt_pk_bf16_f32 v140, v176, v177
	v_cvt_pk_bf16_f32 v141, v178, v179
	v_cvt_pk_bf16_f32 v142, v180, v181
	v_cvt_pk_bf16_f32 v143, v182, v183
	v_cvt_pk_bf16_f32 v144, v184, v185
	v_cvt_pk_bf16_f32 v145, v186, v187
	v_cvt_pk_bf16_f32 v146, v188, v189
	v_cvt_pk_bf16_f32 v147, v190, v191
	ds_write_b64 v194, v[140:141] offset:8704
	ds_write_b64 v194, v[142:143] offset:8720
	ds_write_b64 v194, v[144:145] offset:8736
	ds_write_b64 v194, v[146:147] offset:8752
	s_waitcnt vmcnt(10)
	v_add_u32_e32 v154, s16, v172
	v_add_u32_e32 v155, s16, v173
	ds_read_b32 v116, v155
	ds_read_b32 v117, v154
	ds_read_b32 v118, v154 offset:512
	ds_read_b32 v152, v154 offset:256
	ds_read_b32 v153, v154 offset:768
	ds_write_b128 v170, v[44:47] offset:34816
	ds_write_b128 v170, v[48:51] offset:35088
	ds_write_b128 v170, v[52:55] offset:35360
	ds_write_b128 v170, v[56:59] offset:35632
	ds_write_b128 v170, v[60:63] offset:35904
	ds_write_b128 v170, v[64:67] offset:36176
	ds_write_b128 v170, v[68:71] offset:36448
	ds_write_b128 v170, v[72:75] offset:36720
	v_lshlrev_b32_e32 v120, 16, v76
	v_and_b32_e32 v121, 0xffff0000, v76
	v_lshlrev_b32_e32 v122, 16, v77
	v_and_b32_e32 v123, 0xffff0000, v77
	v_lshlrev_b32_e32 v124, 16, v78
	v_and_b32_e32 v125, 0xffff0000, v78
	v_lshlrev_b32_e32 v126, 16, v79
	v_and_b32_e32 v127, 0xffff0000, v79
	s_waitcnt lgkmcnt(8)
	v_sub_f32_e32 v119, v116, v117
	v_exp_f32_e32 v119, v119
	v_mul_f32_e32 v128, v118, v120
	v_mul_f32_e32 v129, v118, v121
	v_mul_f32_e32 v130, v118, v122
	v_mul_f32_e32 v131, v118, v123
	v_mul_f32_e32 v132, v118, v124
	v_mul_f32_e32 v133, v118, v125
	v_mul_f32_e32 v134, v118, v126
	v_mul_f32_e32 v135, v118, v127
	v_mul_f32_e32 v119, v118, v119
	v_cvt_pk_bf16_f32 v144, v128, v129
	v_cvt_pk_bf16_f32 v145, v130, v131
	v_cvt_pk_bf16_f32 v146, v132, v133
	v_cvt_pk_bf16_f32 v147, v134, v135
	v_mul_f32_e32 v136, v119, v120
	v_mul_f32_e32 v137, v119, v121
	v_mul_f32_e32 v138, v119, v122
	v_mul_f32_e32 v139, v119, v123
	v_mul_f32_e32 v140, v119, v124
	v_mul_f32_e32 v141, v119, v125
	v_mul_f32_e32 v142, v119, v126
	v_mul_f32_e32 v143, v119, v127
	v_cvt_pk_bf16_f32 v148, v136, v137
	v_cvt_pk_bf16_f32 v149, v138, v139
	v_cvt_pk_bf16_f32 v150, v140, v141
	v_cvt_pk_bf16_f32 v151, v142, v143
	ds_write_b128 v171, v[144:147] offset:43008
	ds_write_b128 v197, v[148:151] offset:43008
	v_lshlrev_b32_e32 v120, 16, v80
	v_and_b32_e32 v121, 0xffff0000, v80
	v_lshlrev_b32_e32 v122, 16, v81
	v_and_b32_e32 v123, 0xffff0000, v81
	v_lshlrev_b32_e32 v124, 16, v82
	v_and_b32_e32 v125, 0xffff0000, v82
	v_lshlrev_b32_e32 v126, 16, v83
	v_and_b32_e32 v127, 0xffff0000, v83
	v_sub_f32_e32 v119, v116, v152
	v_exp_f32_e32 v119, v119
	v_mul_f32_e32 v128, v153, v120
	v_mul_f32_e32 v129, v153, v121
	v_mul_f32_e32 v130, v153, v122
	v_mul_f32_e32 v131, v153, v123
	v_mul_f32_e32 v132, v153, v124
	v_mul_f32_e32 v133, v153, v125
	v_mul_f32_e32 v134, v153, v126
	v_mul_f32_e32 v135, v153, v127
	v_mul_f32_e32 v119, v153, v119
	v_cvt_pk_bf16_f32 v144, v128, v129
	v_cvt_pk_bf16_f32 v145, v130, v131
	v_cvt_pk_bf16_f32 v146, v132, v133
	v_cvt_pk_bf16_f32 v147, v134, v135
	v_mul_f32_e32 v136, v119, v120
	v_mul_f32_e32 v137, v119, v121
	v_mul_f32_e32 v138, v119, v122
	v_mul_f32_e32 v139, v119, v123
	v_mul_f32_e32 v140, v119, v124
	v_mul_f32_e32 v141, v119, v125
	v_mul_f32_e32 v142, v119, v126
	v_mul_f32_e32 v143, v119, v127
	v_cvt_pk_bf16_f32 v148, v136, v137
	v_cvt_pk_bf16_f32 v149, v138, v139
	v_cvt_pk_bf16_f32 v150, v140, v141
	v_cvt_pk_bf16_f32 v151, v142, v143
	ds_write_b128 v171, v[144:147] offset:47104
	ds_write_b128 v197, v[148:151] offset:47104
	global_load_dwordx4 v[44:47], v164, s[38:39] offset:0
	global_load_dwordx4 v[48:51], v164, s[38:39] offset:512
	global_load_dwordx4 v[52:55], v164, s[38:39] offset:1024
	global_load_dwordx4 v[56:59], v164, s[38:39] offset:1536
	global_load_dwordx4 v[60:63], v164, s[38:39] offset:2048
	global_load_dwordx4 v[64:67], v164, s[38:39] offset:2560
	global_load_dwordx4 v[68:71], v164, s[38:39] offset:3072
	global_load_dwordx4 v[72:75], v164, s[38:39] offset:3584
	global_load_dwordx4 v[76:79], v168, s[40:41]
	global_load_dwordx4 v[80:83], v169, s[40:41]
	s_add_u32 s38, s38, s46
	s_addc_u32 s39, s39, s55
	s_add_u32 s40, s40, s47
	s_addc_u32 s41, s41, s55
.Lm_stepdone_14:
	s_waitcnt lgkmcnt(0)
	s_barrier
	s_mov_b32 s14, s16
	s_mov_b32 s16, s17
	s_add_u32 s17, s17, 1280
	s_cmpk_eq_u32 s17, 5120
	s_cselect_b32 s17, 0, s17
	s_add_u32 s50, s50, 1
	s_and_b32 s19, s50, 3
	s_lshl_b32 s19, s19, 9
	s_add_u32 s20, s50, 2
	s_and_b32 s20, s20, 3
	s_lshl_b32 s20, s20, 9
	s_cmp_lt_u32 s3, 4
	s_cbranch_scc0 .Lm_hi_23
	v_mov_b32_e32 v223, v165
	v_add_u32_e32 v224, s14, v217
	v_add_u32_e32 v208, s19, v172
	v_add_u32_e32 v216, s14, v209
	v_mov_b32_e32 v225, v222
	v_add_u32_e32 v1, s14, v211
	ds_read_b128 v[176:179], v167 offset:0
	ds_read_b128 v[180:183], v167 offset:32
	ds_read_b128 v[184:187], v167 offset:64
	ds_read_b128 v[188:191], v167 offset:96
	ds_read_b128 v[192:195], v167 offset:128
	ds_read_b128 v[196:199], v167 offset:160
	ds_read_b128 v[200:203], v167 offset:192
	ds_read_b128 v[204:207], v167 offset:224
	ds_read_b128 v[148:151], v223 offset:34816
	ds_read_b128 v[152:155], v223 offset:34848
	ds_read_b128 v[156:159], v223 offset:34880
	ds_read_b128 v[160:163], v223 offset:34912
	s_waitcnt lgkmcnt(11)
	s_waitcnt lgkmcnt(3)
	v_mfma_f32_32x32x16_bf16 v[116:131], v[148:151], v[176:179], 0
	ds_read_b128 v[148:151], v223 offset:34944
	v_fma_f32 v76, v92, v3, v76
	v_fma_f32 v77, v93, v3, v77
	v_fma_f32 v78, v94, v3, v78
	s_waitcnt lgkmcnt(3)
	v_mfma_f32_32x32x16_bf16 v[116:131], v[152:155], v[180:183], v[116:131]
	ds_read_b128 v[152:155], v223 offset:34976
	v_fma_f32 v79, v95, v3, v79
	v_fma_f32 v80, v96, v3, v80
	v_fma_f32 v81, v97, v3, v81
	s_waitcnt lgkmcnt(3)
	v_mfma_f32_32x32x16_bf16 v[116:131], v[156:159], v[184:187], v[116:131]
	ds_read_b128 v[156:159], v223 offset:35008
	v_fma_f32 v82, v98, v3, v82
	v_fma_f32 v83, v99, v3, v83
	v_fma_f32 v84, v100, v3, v84
	s_waitcnt lgkmcnt(3)
	v_mfma_f32_32x32x16_bf16 v[116:131], v[160:163], v[188:191], v[116:131]
	ds_read_b128 v[160:163], v223 offset:35040
	v_fma_f32 v85, v101, v3, v85
	v_fma_f32 v86, v102, v3, v86
	v_fma_f32 v87, v103, v3, v87
	ds_read_b128 v[234:237], v224 offset:0
	ds_read_b128 v[238:241], v224 offset:32
	ds_read_b128 v[242:245], v224 offset:64
	ds_read_b128 v[246:249], v224 offset:96
	ds_read_b32 v250, v1
	s_waitcnt lgkmcnt(8)
	v_mfma_f32_32x32x16_bf16 v[116:131], v[148:151], v[192:195], v[116:131]
	v_fma_f32 v88, v104, v3, v88
	v_fma_f32 v89, v105, v3, v89
	v_fma_f32 v90, v106, v3, v90
	s_waitcnt lgkmcnt(7)
	v_mfma_f32_32x32x16_bf16 v[116:131], v[152:155], v[196:199], v[116:131]
	v_fma_f32 v91, v107, v3, v91
	v_cvt_pk_bf16_f32 v36, v76, v77
	v_cvt_pk_bf16_f32 v37, v78, v79
	s_waitcnt lgkmcnt(6)
	v_mfma_f32_32x32x16_bf16 v[116:131], v[156:159], v[200:203], v[116:131]
	v_cvt_pk_bf16_f32 v38, v80, v81
	v_cvt_pk_bf16_f32 v39, v82, v83
	v_cvt_pk_bf16_f32 v72, v84, v85
	s_waitcnt lgkmcnt(5)
	v_mfma_f32_32x32x16_bf16 v[116:131], v[160:163], v[204:207], v[116:131]
	v_cvt_pk_bf16_f32 v73, v86, v87
	v_cvt_pk_bf16_f32 v74, v88, v89
	v_cvt_pk_bf16_f32 v75, v90, v91
	s_cmp_eq_u32 s52, 1
	s_cbranch_scc1 .Lm_yfin1_28
	ds_write_b64 v168, v[36:37] offset:0
	ds_write_b64 v168, v[38:39] offset:16
	ds_write_b64 v168, v[72:73] offset:32
	ds_write_b64 v168, v[74:75] offset:48
	ds_read_b64_tr_b16 v[36:37], v225 offset:43008
	ds_read_b64_tr_b16 v[38:39], v225 offset:43520
	ds_read_b64_tr_b16 v[72:73], v225 offset:44032
	ds_read_b64_tr_b16 v[74:75], v225 offset:44544
	v_add_u32_e32 v223, s53, v223
	v_add_u32_e32 v208, s54, v208
	v_add_u32_e32 v216, s54, v216
	v_add_u32_e32 v225, s13, v225
	s_waitcnt lgkmcnt(9)
	s_waitcnt lgkmcnt(8)
	ds_read_b128 v[148:151], v223 offset:34816
	ds_read_b128 v[152:155], v223 offset:34848
	ds_read_b128 v[156:159], v223 offset:34880
	ds_read_b128 v[160:163], v223 offset:34912
	s_waitcnt lgkmcnt(3)
	v_mfma_f32_32x32x16_bf16 v[132:147], v[148:151], v[176:179], 0
	ds_read_b128 v[148:151], v223 offset:34944
	ds_read_b128 v[92:95], v169
	ds_read_b128 v[96:99], v169 offset:1280
	v_sub_f32_e32 v234, v250, v234
	v_sub_f32_e32 v235, v250, v235
	v_sub_f32_e32 v236, v250, v236
	v_sub_f32_e32 v237, v250, v237
	v_sub_f32_e32 v238, v250, v238
	v_sub_f32_e32 v239, v250, v239
	v_sub_f32_e32 v240, v250, v240
	v_sub_f32_e32 v241, v250, v241
	v_sub_f32_e32 v242, v250, v242
	s_waitcnt lgkmcnt(5)
	v_mfma_f32_32x32x16_bf16 v[132:147], v[152:155], v[180:183], v[132:147]
	ds_read_b128 v[152:155], v223 offset:34976
	v_sub_f32_e32 v243, v250, v243
	v_sub_f32_e32 v244, v250, v244
	v_sub_f32_e32 v245, v250, v245
	v_sub_f32_e32 v246, v250, v246
	v_sub_f32_e32 v247, v250, v247
	v_sub_f32_e32 v248, v250, v248
	v_sub_f32_e32 v249, v250, v249
	v_exp_f32_e32 v234, v234
	v_exp_f32_e32 v235, v235
	s_waitcnt lgkmcnt(5)
	v_mfma_f32_32x32x16_bf16 v[132:147], v[156:159], v[184:187], v[132:147]
	ds_read_b128 v[156:159], v223 offset:35008
	v_exp_f32_e32 v236, v236
	v_exp_f32_e32 v237, v237
	v_exp_f32_e32 v238, v238
	v_exp_f32_e32 v239, v239
	v_exp_f32_e32 v240, v240
	v_exp_f32_e32 v241, v241
	v_exp_f32_e32 v242, v242
	v_exp_f32_e32 v243, v243
	v_exp_f32_e32 v244, v244
	s_waitcnt lgkmcnt(5)
	v_mfma_f32_32x32x16_bf16 v[132:147], v[160:163], v[188:191], v[132:147]
	ds_read_b128 v[160:163], v223 offset:35040
	s_waitcnt lgkmcnt(3)
	global_store_dwordx4 v170, v[92:95], s[44:45]
	global_store_dwordx4 v171, v[96:99], s[44:45]
	s_cmp_lg_u32 s50, 0
	s_cselect_b32 s4, s49, 0
	s_cselect_b32 s5, s55, 0
	s_add_u32 s44, s44, s4
	s_addc_u32 s45, s45, s5
	s_waitcnt vmcnt(12)
	v_exp_f32_e32 v245, v245
	v_exp_f32_e32 v246, v246
	v_exp_f32_e32 v247, v247
	v_exp_f32_e32 v248, v248
	v_exp_f32_e32 v249, v249
	v_mul_f32_e32 v116, v116, v234
	v_mul_f32_e32 v117, v117, v235
	v_mul_f32_e32 v118, v118, v236
	v_mul_f32_e32 v119, v119, v237
	v_mfma_f32_32x32x16_bf16 v[132:147], v[148:151], v[192:195], v[132:147]
	ds_write_b128 v166, v[4:7] offset:0
	ds_write_b128 v166, v[8:11] offset:272
	v_mul_f32_e32 v120, v120, v238
	v_mul_f32_e32 v121, v121, v239
	v_mul_f32_e32 v122, v122, v240
	v_mul_f32_e32 v123, v123, v241
	v_mul_f32_e32 v124, v124, v242
	v_mul_f32_e32 v125, v125, v243
	v_mul_f32_e32 v126, v126, v244
	v_mul_f32_e32 v127, v127, v245
	v_mul_f32_e32 v128, v128, v246
	s_waitcnt lgkmcnt(4)
	v_mfma_f32_32x32x16_bf16 v[132:147], v[152:155], v[196:199], v[132:147]
	ds_write_b128 v166, v[12:15] offset:544
	ds_write_b128 v166, v[16:19] offset:816
	v_mul_f32_e32 v129, v129, v247
	v_mul_f32_e32 v130, v130, v248
	v_mul_f32_e32 v131, v131, v249
	v_cndmask_b32_e64 v116, 0, v116, s[64:65]
	v_cndmask_b32_e64 v117, 0, v117, s[66:67]
	v_cndmask_b32_e64 v118, 0, v118, s[68:69]
	v_cndmask_b32_e64 v119, 0, v119, s[70:71]
	v_cndmask_b32_e64 v120, 0, v120, s[72:73]
	v_cndmask_b32_e64 v121, 0, v121, s[74:75]
	s_waitcnt lgkmcnt(5)
	v_mfma_f32_32x32x16_bf16 v[132:147], v[156:159], v[200:203], v[132:147]
	ds_write_b128 v166, v[20:23] offset:1088
	ds_write_b128 v166, v[24:27] offset:1360
	v_cndmask_b32_e64 v122, 0, v122, s[76:77]
	v_cndmask_b32_e64 v123, 0, v123, s[78:79]
	v_cndmask_b32_e64 v124, 0, v124, s[80:81]
	v_cndmask_b32_e64 v125, 0, v125, s[82:83]
	v_cndmask_b32_e64 v126, 0, v126, s[84:85]
	v_cndmask_b32_e64 v127, 0, v127, s[86:87]
	v_cndmask_b32_e64 v128, 0, v128, s[88:89]
	v_cndmask_b32_e64 v129, 0, v129, s[90:91]
	v_cndmask_b32_e64 v130, 0, v130, s[92:93]
	s_waitcnt lgkmcnt(6)
	v_mfma_f32_32x32x16_bf16 v[132:147], v[160:163], v[204:207], v[132:147]
	ds_write_b128 v166, v[28:31] offset:1632
	ds_write_b128 v166, v[32:35] offset:1904
	v_cndmask_b32_e64 v131, 0, v131, s[94:95]
	v_cvt_pk_bf16_f32 v116, v116, v117
	v_cvt_pk_bf16_f32 v117, v118, v119
	v_cvt_pk_bf16_f32 v118, v120, v121
	v_cvt_pk_bf16_f32 v119, v122, v123
	v_cvt_pk_bf16_f32 v120, v124, v125
	v_cvt_pk_bf16_f32 v121, v126, v127
	v_cvt_pk_bf16_f32 v122, v128, v129
	v_cvt_pk_bf16_f32 v123, v130, v131
	global_load_dwordx4 v[4:7], v164, s[38:39] offset:0
	global_load_dwordx4 v[8:11], v164, s[38:39] offset:512
	global_load_dwordx4 v[12:15], v164, s[38:39] offset:1024
	global_load_dwordx4 v[16:19], v164, s[38:39] offset:1536
	global_load_dwordx4 v[20:23], v164, s[38:39] offset:2048
	global_load_dwordx4 v[24:27], v164, s[38:39] offset:2560
	global_load_dwordx4 v[28:31], v164, s[38:39] offset:3072
	global_load_dwordx4 v[32:35], v164, s[38:39] offset:3584
	s_add_u32 s38, s38, s46
	s_addc_u32 s39, s39, s55
	s_waitcnt lgkmcnt(0)
	ds_read_b128 v[234:237], v208 offset:0
	ds_read_b128 v[238:241], v208 offset:32
	ds_read_b128 v[242:245], v208 offset:64
	ds_read_b128 v[246:249], v208 offset:96
	ds_read_b32 v251, v216
	v_mfma_f32_32x32x16_bf16 v[76:91], v[36:39], v[116:119], 0
	v_mfma_f32_32x32x16_bf16 v[76:91], v[72:75], v[120:123], v[76:91]
	s_cmp_eq_u32 s52, 2
	s_cbranch_scc1 .Lm_yfin2_29
	ds_read_b64_tr_b16 v[36:37], v225 offset:43008
	ds_read_b64_tr_b16 v[38:39], v225 offset:43520
	ds_read_b64_tr_b16 v[72:73], v225 offset:44032
	ds_read_b64_tr_b16 v[74:75], v225 offset:44544
	v_add_u32_e32 v223, s53, v223
	v_add_u32_e32 v208, s54, v208
	v_add_u32_e32 v216, s54, v216
	v_add_u32_e32 v225, s13, v225
	s_waitcnt lgkmcnt(4)
	ds_read_b128 v[148:151], v223 offset:34816
	ds_read_b128 v[152:155], v223 offset:34848
	ds_read_b128 v[156:159], v223 offset:34880
	ds_read_b128 v[160:163], v223 offset:34912
	s_waitcnt lgkmcnt(3)
	v_mfma_f32_32x32x16_bf16 v[116:131], v[148:151], v[176:179], 0
	ds_read_b128 v[148:151], v223 offset:34944
	v_sub_f32_e32 v2, v250, v251
	v_exp_f32_e32 v2, v2
	s_nop 0
	v_mul_f32_e32 v234, v234, v2
	v_mul_f32_e32 v235, v235, v2
	s_waitcnt lgkmcnt(3)
	v_mfma_f32_32x32x16_bf16 v[116:131], v[152:155], v[180:183], v[116:131]
	ds_read_b128 v[152:155], v223 offset:34976
	v_mul_f32_e32 v236, v236, v2
	v_mul_f32_e32 v237, v237, v2
	v_mul_f32_e32 v238, v238, v2
	v_mul_f32_e32 v239, v239, v2
	v_mul_f32_e32 v240, v240, v2
	s_waitcnt lgkmcnt(3)
	v_mfma_f32_32x32x16_bf16 v[116:131], v[156:159], v[184:187], v[116:131]
	ds_read_b128 v[156:159], v223 offset:35008
	v_mul_f32_e32 v241, v241, v2
	v_mul_f32_e32 v242, v242, v2
	v_mul_f32_e32 v243, v243, v2
	v_mul_f32_e32 v244, v244, v2
	v_mul_f32_e32 v245, v245, v2
	v_mul_f32_e32 v246, v246, v2
	s_waitcnt lgkmcnt(3)
	v_mfma_f32_32x32x16_bf16 v[116:131], v[160:163], v[188:191], v[116:131]
	ds_read_b128 v[160:163], v223 offset:35040
	v_mul_f32_e32 v247, v247, v2
	v_mul_f32_e32 v248, v248, v2
	v_mul_f32_e32 v249, v249, v2
	v_mul_f32_e32 v132, v132, v234
	v_mul_f32_e32 v133, v133, v235
	s_waitcnt lgkmcnt(3)
	v_mfma_f32_32x32x16_bf16 v[116:131], v[148:151], v[192:195], v[116:131]
	v_mul_f32_e32 v134, v134, v236
	v_mul_f32_e32 v135, v135, v237
	v_mul_f32_e32 v136, v136, v238
	v_mul_f32_e32 v137, v137, v239
	v_mul_f32_e32 v138, v138, v240
	s_waitcnt lgkmcnt(2)
	v_mfma_f32_32x32x16_bf16 v[116:131], v[152:155], v[196:199], v[116:131]
	v_mul_f32_e32 v139, v139, v241
	v_mul_f32_e32 v140, v140, v242
	v_mul_f32_e32 v141, v141, v243
	v_mul_f32_e32 v142, v142, v244
	v_mul_f32_e32 v143, v143, v245
	v_mul_f32_e32 v144, v144, v246
	s_waitcnt lgkmcnt(1)
	v_mfma_f32_32x32x16_bf16 v[116:131], v[156:159], v[200:203], v[116:131]
	v_mul_f32_e32 v145, v145, v247
	v_mul_f32_e32 v146, v146, v248
	v_mul_f32_e32 v147, v147, v249
	v_cvt_pk_bf16_f32 v132, v132, v133
	v_cvt_pk_bf16_f32 v133, v134, v135
	s_waitcnt lgkmcnt(0)
	v_mfma_f32_32x32x16_bf16 v[116:131], v[160:163], v[204:207], v[116:131]
	v_cvt_pk_bf16_f32 v134, v136, v137
	v_cvt_pk_bf16_f32 v135, v138, v139
	v_cvt_pk_bf16_f32 v136, v140, v141
	v_cvt_pk_bf16_f32 v137, v142, v143
	v_cvt_pk_bf16_f32 v138, v144, v145
	v_cvt_pk_bf16_f32 v139, v146, v147
	ds_read_b128 v[234:237], v208 offset:0
	ds_read_b128 v[238:241], v208 offset:32
	ds_read_b128 v[242:245], v208 offset:64
	ds_read_b128 v[246:249], v208 offset:96
	ds_read_b32 v251, v216
	v_mfma_f32_32x32x16_bf16 v[76:91], v[36:39], v[132:135], v[76:91]
	v_mfma_f32_32x32x16_bf16 v[76:91], v[72:75], v[136:139], v[76:91]
	s_cmp_eq_u32 s52, 3
	s_cbranch_scc1 .Lm_yfin3_30
	ds_read_b64_tr_b16 v[36:37], v225 offset:43008
	ds_read_b64_tr_b16 v[38:39], v225 offset:43520
	ds_read_b64_tr_b16 v[72:73], v225 offset:44032
	ds_read_b64_tr_b16 v[74:75], v225 offset:44544
	v_add_u32_e32 v223, s53, v223
	v_add_u32_e32 v208, s54, v208
	v_add_u32_e32 v216, s54, v216
	v_add_u32_e32 v225, s13, v225
	s_waitcnt lgkmcnt(4)
	ds_read_b128 v[148:151], v223 offset:34816
	ds_read_b128 v[152:155], v223 offset:34848
	ds_read_b128 v[156:159], v223 offset:34880
	ds_read_b128 v[160:163], v223 offset:34912
	s_waitcnt lgkmcnt(3)
	v_mfma_f32_32x32x16_bf16 v[132:147], v[148:151], v[176:179], 0
	ds_read_b128 v[148:151], v223 offset:34944
	v_sub_f32_e32 v2, v250, v251
	v_exp_f32_e32 v2, v2
	s_nop 0
	v_mul_f32_e32 v234, v234, v2
	v_mul_f32_e32 v235, v235, v2
	s_waitcnt lgkmcnt(3)
	v_mfma_f32_32x32x16_bf16 v[132:147], v[152:155], v[180:183], v[132:147]
	ds_read_b128 v[152:155], v223 offset:34976
	v_mul_f32_e32 v236, v236, v2
	v_mul_f32_e32 v237, v237, v2
	v_mul_f32_e32 v238, v238, v2
	v_mul_f32_e32 v239, v239, v2
	v_mul_f32_e32 v240, v240, v2
	s_waitcnt lgkmcnt(3)
	v_mfma_f32_32x32x16_bf16 v[132:147], v[156:159], v[184:187], v[132:147]
	ds_read_b128 v[156:159], v223 offset:35008
	v_mul_f32_e32 v241, v241, v2
	v_mul_f32_e32 v242, v242, v2
	v_mul_f32_e32 v243, v243, v2
	v_mul_f32_e32 v244, v244, v2
	v_mul_f32_e32 v245, v245, v2
	v_mul_f32_e32 v246, v246, v2
	s_waitcnt lgkmcnt(3)
	v_mfma_f32_32x32x16_bf16 v[132:147], v[160:163], v[188:191], v[132:147]
	ds_read_b128 v[160:163], v223 offset:35040
	v_mul_f32_e32 v247, v247, v2
	v_mul_f32_e32 v248, v248, v2
	v_mul_f32_e32 v249, v249, v2
	v_mul_f32_e32 v116, v116, v234
	v_mul_f32_e32 v117, v117, v235
	s_waitcnt lgkmcnt(3)
	v_mfma_f32_32x32x16_bf16 v[132:147], v[148:151], v[192:195], v[132:147]
	v_mul_f32_e32 v118, v118, v236
	v_mul_f32_e32 v119, v119, v237
	v_mul_f32_e32 v120, v120, v238
	v_mul_f32_e32 v121, v121, v239
	v_mul_f32_e32 v122, v122, v240
	s_waitcnt lgkmcnt(2)
	v_mfma_f32_32x32x16_bf16 v[132:147], v[152:155], v[196:199], v[132:147]
	v_mul_f32_e32 v123, v123, v241
	v_mul_f32_e32 v124, v124, v242
	v_mul_f32_e32 v125, v125, v243
	v_mul_f32_e32 v126, v126, v244
	v_mul_f32_e32 v127, v127, v245
	v_mul_f32_e32 v128, v128, v246
	s_waitcnt lgkmcnt(1)
	v_mfma_f32_32x32x16_bf16 v[132:147], v[156:159], v[200:203], v[132:147]
	v_mul_f32_e32 v129, v129, v247
	v_mul_f32_e32 v130, v130, v248
	v_mul_f32_e32 v131, v131, v249
	v_cvt_pk_bf16_f32 v116, v116, v117
	v_cvt_pk_bf16_f32 v117, v118, v119
	s_waitcnt lgkmcnt(0)
	v_mfma_f32_32x32x16_bf16 v[132:147], v[160:163], v[204:207], v[132:147]
	v_cvt_pk_bf16_f32 v118, v120, v121
	v_cvt_pk_bf16_f32 v119, v122, v123
	v_cvt_pk_bf16_f32 v120, v124, v125
	v_cvt_pk_bf16_f32 v121, v126, v127
	v_cvt_pk_bf16_f32 v122, v128, v129
	v_cvt_pk_bf16_f32 v123, v130, v131
	ds_read_b128 v[234:237], v208 offset:0
	ds_read_b128 v[238:241], v208 offset:32
	ds_read_b128 v[242:245], v208 offset:64
	ds_read_b128 v[246:249], v208 offset:96
	ds_read_b32 v251, v216
	v_mfma_f32_32x32x16_bf16 v[76:91], v[36:39], v[116:119], v[76:91]
	v_mfma_f32_32x32x16_bf16 v[76:91], v[72:75], v[120:123], v[76:91]
	ds_read_b64_tr_b16 v[36:37], v225 offset:43008
	ds_read_b64_tr_b16 v[38:39], v225 offset:43520
	ds_read_b64_tr_b16 v[72:73], v225 offset:44032
	ds_read_b64_tr_b16 v[74:75], v225 offset:44544
	s_waitcnt lgkmcnt(4)
	ds_read_b128 v[148:151], v210 offset:8704
	ds_read_b128 v[152:155], v210 offset:8736
	ds_read_b128 v[156:159], v210 offset:8768
	ds_read_b128 v[160:163], v210 offset:8800
	s_waitcnt lgkmcnt(3)
	v_mfma_f32_32x32x16_bf16 v[92:107], v[148:151], v[176:179], 0
	ds_read_b128 v[148:151], v210 offset:8832
	v_sub_f32_e32 v2, v250, v251
	v_exp_f32_e32 v2, v2
	s_nop 0
	v_mul_f32_e32 v234, v234, v2
	v_mul_f32_e32 v235, v235, v2
	s_waitcnt lgkmcnt(3)
	v_mfma_f32_32x32x16_bf16 v[92:107], v[152:155], v[180:183], v[92:107]
	ds_read_b128 v[152:155], v210 offset:8864
	v_mul_f32_e32 v236, v236, v2
	v_mul_f32_e32 v237, v237, v2
	v_mul_f32_e32 v238, v238, v2
	v_mul_f32_e32 v239, v239, v2
	v_mul_f32_e32 v240, v240, v2
	s_waitcnt lgkmcnt(3)
	v_mfma_f32_32x32x16_bf16 v[92:107], v[156:159], v[184:187], v[92:107]
	ds_read_b128 v[156:159], v210 offset:8896
	v_mul_f32_e32 v241, v241, v2
	v_mul_f32_e32 v242, v242, v2
	v_mul_f32_e32 v243, v243, v2
	v_mul_f32_e32 v244, v244, v2
	v_mul_f32_e32 v245, v245, v2
	v_mul_f32_e32 v246, v246, v2
	s_waitcnt lgkmcnt(3)
	v_mfma_f32_32x32x16_bf16 v[92:107], v[160:163], v[188:191], v[92:107]
	ds_read_b128 v[160:163], v210 offset:8928
	v_mul_f32_e32 v247, v247, v2
	v_mul_f32_e32 v248, v248, v2
	v_mul_f32_e32 v249, v249, v2
	v_mul_f32_e32 v132, v132, v234
	v_mul_f32_e32 v133, v133, v235
	s_waitcnt lgkmcnt(3)
	v_mfma_f32_32x32x16_bf16 v[92:107], v[148:151], v[192:195], v[92:107]
	v_mul_f32_e32 v134, v134, v236
	v_mul_f32_e32 v135, v135, v237
	v_mul_f32_e32 v136, v136, v238
	v_mul_f32_e32 v137, v137, v239
	v_mul_f32_e32 v138, v138, v240
	s_waitcnt lgkmcnt(2)
	v_mfma_f32_32x32x16_bf16 v[92:107], v[152:155], v[196:199], v[92:107]
	v_mul_f32_e32 v139, v139, v241
	v_mul_f32_e32 v140, v140, v242
	v_mul_f32_e32 v141, v141, v243
	v_mul_f32_e32 v142, v142, v244
	v_mul_f32_e32 v143, v143, v245
	v_mul_f32_e32 v144, v144, v246
	s_waitcnt lgkmcnt(1)
	v_mfma_f32_32x32x16_bf16 v[92:107], v[156:159], v[200:203], v[92:107]
	v_mul_f32_e32 v145, v145, v247
	v_mul_f32_e32 v146, v146, v248
	v_mul_f32_e32 v147, v147, v249
	v_cvt_pk_bf16_f32 v132, v132, v133
	v_cvt_pk_bf16_f32 v133, v134, v135
	s_waitcnt lgkmcnt(0)
	v_mfma_f32_32x32x16_bf16 v[92:107], v[160:163], v[204:207], v[92:107]
	v_cvt_pk_bf16_f32 v134, v136, v137
	v_cvt_pk_bf16_f32 v135, v138, v139
	v_cvt_pk_bf16_f32 v136, v140, v141
	v_cvt_pk_bf16_f32 v137, v142, v143
	v_cvt_pk_bf16_f32 v138, v144, v145
	v_cvt_pk_bf16_f32 v139, v146, v147
	v_mfma_f32_32x32x16_bf16 v[76:91], v[36:39], v[132:135], v[76:91]
	v_mfma_f32_32x32x16_bf16 v[76:91], v[72:75], v[136:139], v[76:91]
	s_branch .Lm_ydone_31
.Lm_yfin1_28:
	ds_write_b64 v168, v[36:37] offset:0
	ds_write_b64 v168, v[38:39] offset:16
	ds_write_b64 v168, v[72:73] offset:32
	ds_write_b64 v168, v[74:75] offset:48
	s_waitcnt lgkmcnt(0)
	ds_read_b128 v[92:95], v169
	ds_read_b128 v[96:99], v169 offset:1280
	s_waitcnt lgkmcnt(0)
	global_store_dwordx4 v170, v[92:95], s[44:45]
	global_store_dwordx4 v171, v[96:99], s[44:45]
	s_cmp_lg_u32 s50, 0
	s_cselect_b32 s4, s49, 0
	s_cselect_b32 s5, s55, 0
	s_add_u32 s44, s44, s4
	s_addc_u32 s45, s45, s5
	s_waitcnt vmcnt(16)
	ds_write_b128 v166, v[4:7] offset:0
	ds_write_b128 v166, v[8:11] offset:272
	ds_write_b128 v166, v[12:15] offset:544
	ds_write_b128 v166, v[16:19] offset:816
	ds_write_b128 v166, v[20:23] offset:1088
	ds_write_b128 v166, v[24:27] offset:1360
	ds_write_b128 v166, v[28:31] offset:1632
	ds_write_b128 v166, v[32:35] offset:1904
	global_load_dwordx4 v[4:7], v164, s[38:39] offset:0
	global_load_dwordx4 v[8:11], v164, s[38:39] offset:512
	global_load_dwordx4 v[12:15], v164, s[38:39] offset:1024
	global_load_dwordx4 v[16:19], v164, s[38:39] offset:1536
	global_load_dwordx4 v[20:23], v164, s[38:39] offset:2048
	global_load_dwordx4 v[24:27], v164, s[38:39] offset:2560
	global_load_dwordx4 v[28:31], v164, s[38:39] offset:3072
	global_load_dwordx4 v[32:35], v164, s[38:39] offset:3584
	s_add_u32 s38, s38, s46
	s_addc_u32 s39, s39, s55
	s_waitcnt lgkmcnt(0)
	ds_read_b64_tr_b16 v[36:37], v225 offset:43008
	ds_read_b64_tr_b16 v[38:39], v225 offset:43520
	ds_read_b64_tr_b16 v[72:73], v225 offset:44032
	ds_read_b64_tr_b16 v[74:75], v225 offset:44544
	ds_read_b128 v[148:151], v210 offset:8704
	ds_read_b128 v[152:155], v210 offset:8736
	ds_read_b128 v[156:159], v210 offset:8768
	ds_read_b128 v[160:163], v210 offset:8800
	s_waitcnt lgkmcnt(3)
	v_mfma_f32_32x32x16_bf16 v[92:107], v[148:151], v[176:179], 0
	ds_read_b128 v[148:151], v210 offset:8832
	v_sub_f32_e32 v234, v250, v234
	v_sub_f32_e32 v235, v250, v235
	v_sub_f32_e32 v236, v250, v236
	v_sub_f32_e32 v237, v250, v237
	v_sub_f32_e32 v238, v250, v238
	v_sub_f32_e32 v239, v250, v239
	v_sub_f32_e32 v240, v250, v240
	v_sub_f32_e32 v241, v250, v241
	v_sub_f32_e32 v242, v250, v242
	s_waitcnt lgkmcnt(3)
	v_mfma_f32_32x32x16_bf16 v[92:107], v[152:155], v[180:183], v[92:107]
	ds_read_b128 v[152:155], v210 offset:8864
	v_sub_f32_e32 v243, v250, v243
	v_sub_f32_e32 v244, v250, v244
	v_sub_f32_e32 v245, v250, v245
	v_sub_f32_e32 v246, v250, v246
	v_sub_f32_e32 v247, v250, v247
	v_sub_f32_e32 v248, v250, v248
	v_sub_f32_e32 v249, v250, v249
	v_exp_f32_e32 v234, v234
	v_exp_f32_e32 v235, v235
	s_waitcnt lgkmcnt(3)
	v_mfma_f32_32x32x16_bf16 v[92:107], v[156:159], v[184:187], v[92:107]
	ds_read_b128 v[156:159], v210 offset:8896
	v_exp_f32_e32 v236, v236
	v_exp_f32_e32 v237, v237
	v_exp_f32_e32 v238, v238
	v_exp_f32_e32 v239, v239
	v_exp_f32_e32 v240, v240
	v_exp_f32_e32 v241, v241
	v_exp_f32_e32 v242, v242
	v_exp_f32_e32 v243, v243
	v_exp_f32_e32 v244, v244
	s_waitcnt lgkmcnt(3)
	v_mfma_f32_32x32x16_bf16 v[92:107], v[160:163], v[188:191], v[92:107]
	ds_read_b128 v[160:163], v210 offset:8928
	v_exp_f32_e32 v245, v245
	v_exp_f32_e32 v246, v246
	v_exp_f32_e32 v247, v247
	v_exp_f32_e32 v248, v248
	v_exp_f32_e32 v249, v249
	v_mul_f32_e32 v116, v116, v234
	v_mul_f32_e32 v117, v117, v235
	v_mul_f32_e32 v118, v118, v236
	v_mul_f32_e32 v119, v119, v237
	s_waitcnt lgkmcnt(3)
	v_mfma_f32_32x32x16_bf16 v[92:107], v[148:151], v[192:195], v[92:107]
	v_mul_f32_e32 v120, v120, v238
	v_mul_f32_e32 v121, v121, v239
	v_mul_f32_e32 v122, v122, v240
	v_mul_f32_e32 v123, v123, v241
	v_mul_f32_e32 v124, v124, v242
	v_mul_f32_e32 v125, v125, v243
	v_mul_f32_e32 v126, v126, v244
	v_mul_f32_e32 v127, v127, v245
	v_mul_f32_e32 v128, v128, v246
	s_waitcnt lgkmcnt(2)
	v_mfma_f32_32x32x16_bf16 v[92:107], v[152:155], v[196:199], v[92:107]
	v_mul_f32_e32 v129, v129, v247
	v_mul_f32_e32 v130, v130, v248
	v_mul_f32_e32 v131, v131, v249
	v_cndmask_b32_e64 v116, 0, v116, s[64:65]
	v_cndmask_b32_e64 v117, 0, v117, s[66:67]
	v_cndmask_b32_e64 v118, 0, v118, s[68:69]
	v_cndmask_b32_e64 v119, 0, v119, s[70:71]
	v_cndmask_b32_e64 v120, 0, v120, s[72:73]
	v_cndmask_b32_e64 v121, 0, v121, s[74:75]
	s_waitcnt lgkmcnt(1)
	v_mfma_f32_32x32x16_bf16 v[92:107], v[156:159], v[200:203], v[92:107]
	v_cndmask_b32_e64 v122, 0, v122, s[76:77]
	v_cndmask_b32_e64 v123, 0, v123, s[78:79]
	v_cndmask_b32_e64 v124, 0, v124, s[80:81]
	v_cndmask_b32_e64 v125, 0, v125, s[82:83]
	v_cndmask_b32_e64 v126, 0, v126, s[84:85]
	v_cndmask_b32_e64 v127, 0, v127, s[86:87]
	v_cndmask_b32_e64 v128, 0, v128, s[88:89]
	v_cndmask_b32_e64 v129, 0, v129, s[90:91]
	v_cndmask_b32_e64 v130, 0, v130, s[92:93]
	s_waitcnt lgkmcnt(0)
	v_mfma_f32_32x32x16_bf16 v[92:107], v[160:163], v[204:207], v[92:107]
	v_cndmask_b32_e64 v131, 0, v131, s[94:95]
	v_cvt_pk_bf16_f32 v116, v116, v117
	v_cvt_pk_bf16_f32 v117, v118, v119
	v_cvt_pk_bf16_f32 v118, v120, v121
	v_cvt_pk_bf16_f32 v119, v122, v123
	v_cvt_pk_bf16_f32 v120, v124, v125
	v_cvt_pk_bf16_f32 v121, v126, v127
	v_cvt_pk_bf16_f32 v122, v128, v129
	v_cvt_pk_bf16_f32 v123, v130, v131
	v_mfma_f32_32x32x16_bf16 v[76:91], v[36:39], v[116:119], 0
	v_mfma_f32_32x32x16_bf16 v[76:91], v[72:75], v[120:123], v[76:91]
	s_waitcnt vmcnt(10)
	v_mul_f32_e32 v132, s62, v146
	v_mul_f32_e32 v133, s62, v147
	v_add_f32_e32 v134, v132, v133
	v_and_b32_e32 v140, 63, v175
	v_lshrrev_b32_e32 v142, 4, v140
	v_add_f32_dpp v134, v134, v134 row_shr:1 row_mask:0xf bank_mask:0xf bound_ctrl:0
	s_nop 1
	v_add_f32_dpp v134, v134, v134 row_shr:2 row_mask:0xf bank_mask:0xf bound_ctrl:0
	s_nop 1
	v_add_f32_dpp v134, v134, v134 row_shr:4 row_mask:0xf bank_mask:0xf bound_ctrl:0
	s_nop 1
	v_add_f32_dpp v134, v134, v134 row_shr:8 row_mask:0xf bank_mask:0xf bound_ctrl:0
	s_nop 1
	v_add_f32_dpp v134, v134, v134 row_bcast:15 row_mask:0xa bank_mask:0xf
	s_nop 1
	v_add_f32_dpp v134, v134, v134 row_bcast:31 row_mask:0xc bank_mask:0xf
	v_lshlrev_b32_e32 v140, 3, v140
	v_lshlrev_b32_e32 v142, 7, v142
	v_readlane_b32 s97, v134, 63
	v_sub_f32_e32 v138, v134, v133
	v_mov_b32_e32 v139, v134
	v_add_u32_e32 v143, 0x1d800, v140
	v_add_u32_e32 v143, s20, v143
	s_cmp_eq_u32 s51, 0
	s_cbranch_scc1 .Lm_scanf_32
	v_sub_f32_e32 v138, s97, v138
	v_sub_f32_e32 v139, s97, v139
	v_fma_f32 v138, v146, s62, v138
	v_fma_f32 v139, v147, s62, v139

.Lm_yfin2_29:
	ds_read_b64_tr_b16 v[36:37], v225 offset:43008
	ds_read_b64_tr_b16 v[38:39], v225 offset:43520
	ds_read_b64_tr_b16 v[72:73], v225 offset:44032
	ds_read_b64_tr_b16 v[74:75], v225 offset:44544
	s_waitcnt lgkmcnt(4)
	ds_read_b128 v[148:151], v210 offset:8704
	ds_read_b128 v[152:155], v210 offset:8736
	ds_read_b128 v[156:159], v210 offset:8768
	ds_read_b128 v[160:163], v210 offset:8800
	s_waitcnt lgkmcnt(3)
	v_mfma_f32_32x32x16_bf16 v[92:107], v[148:151], v[176:179], 0
	ds_read_b128 v[148:151], v210 offset:8832
	v_sub_f32_e32 v2, v250, v251
	v_exp_f32_e32 v2, v2
	s_nop 0
	v_mul_f32_e32 v234, v234, v2
	v_mul_f32_e32 v235, v235, v2
	s_waitcnt lgkmcnt(3)
	v_mfma_f32_32x32x16_bf16 v[92:107], v[152:155], v[180:183], v[92:107]
	ds_read_b128 v[152:155], v210 offset:8864
	v_mul_f32_e32 v236, v236, v2
	v_mul_f32_e32 v237, v237, v2
	v_mul_f32_e32 v238, v238, v2
	v_mul_f32_e32 v239, v239, v2
	v_mul_f32_e32 v240, v240, v2
	s_waitcnt lgkmcnt(3)
	v_mfma_f32_32x32x16_bf16 v[92:107], v[156:159], v[184:187], v[92:107]
	ds_read_b128 v[156:159], v210 offset:8896
	v_mul_f32_e32 v241, v241, v2
	v_mul_f32_e32 v242, v242, v2
	v_mul_f32_e32 v243, v243, v2
	v_mul_f32_e32 v244, v244, v2
	v_mul_f32_e32 v245, v245, v2
	v_mul_f32_e32 v246, v246, v2
	s_waitcnt lgkmcnt(3)
	v_mfma_f32_32x32x16_bf16 v[92:107], v[160:163], v[188:191], v[92:107]
	ds_read_b128 v[160:163], v210 offset:8928
	v_mul_f32_e32 v247, v247, v2
	v_mul_f32_e32 v248, v248, v2
	v_mul_f32_e32 v249, v249, v2
	v_mul_f32_e32 v132, v132, v234
	v_mul_f32_e32 v133, v133, v235
	s_waitcnt lgkmcnt(3)
	v_mfma_f32_32x32x16_bf16 v[92:107], v[148:151], v[192:195], v[92:107]
	v_mul_f32_e32 v134, v134, v236
	v_mul_f32_e32 v135, v135, v237
	v_mul_f32_e32 v136, v136, v238
	v_mul_f32_e32 v137, v137, v239
	v_mul_f32_e32 v138, v138, v240
	s_waitcnt lgkmcnt(2)
	v_mfma_f32_32x32x16_bf16 v[92:107], v[152:155], v[196:199], v[92:107]
	v_mul_f32_e32 v139, v139, v241
	v_mul_f32_e32 v140, v140, v242
	v_mul_f32_e32 v141, v141, v243
	v_mul_f32_e32 v142, v142, v244
	v_mul_f32_e32 v143, v143, v245
	v_mul_f32_e32 v144, v144, v246
	s_waitcnt lgkmcnt(1)
	v_mfma_f32_32x32x16_bf16 v[92:107], v[156:159], v[200:203], v[92:107]
	v_mul_f32_e32 v145, v145, v247
	v_mul_f32_e32 v146, v146, v248
	v_mul_f32_e32 v147, v147, v249
	v_cvt_pk_bf16_f32 v132, v132, v133
	v_cvt_pk_bf16_f32 v133, v134, v135
	s_waitcnt lgkmcnt(0)
	v_mfma_f32_32x32x16_bf16 v[92:107], v[160:163], v[204:207], v[92:107]
	v_cvt_pk_bf16_f32 v134, v136, v137
	v_cvt_pk_bf16_f32 v135, v138, v139
	v_cvt_pk_bf16_f32 v136, v140, v141
	v_cvt_pk_bf16_f32 v137, v142, v143
	v_cvt_pk_bf16_f32 v138, v144, v145
	v_cvt_pk_bf16_f32 v139, v146, v147
	v_mfma_f32_32x32x16_bf16 v[76:91], v[36:39], v[132:135], v[76:91]
	v_mfma_f32_32x32x16_bf16 v[76:91], v[72:75], v[136:139], v[76:91]
	s_branch .Lm_ydone_31
.Lm_yfin3_30:
	ds_read_b64_tr_b16 v[36:37], v225 offset:43008
	ds_read_b64_tr_b16 v[38:39], v225 offset:43520
	ds_read_b64_tr_b16 v[72:73], v225 offset:44032
	ds_read_b64_tr_b16 v[74:75], v225 offset:44544
	s_waitcnt lgkmcnt(4)
	ds_read_b128 v[148:151], v210 offset:8704
	ds_read_b128 v[152:155], v210 offset:8736
	ds_read_b128 v[156:159], v210 offset:8768
	ds_read_b128 v[160:163], v210 offset:8800
	s_waitcnt lgkmcnt(3)
	v_mfma_f32_32x32x16_bf16 v[92:107], v[148:151], v[176:179], 0
	ds_read_b128 v[148:151], v210 offset:8832
	v_sub_f32_e32 v2, v250, v251
	v_exp_f32_e32 v2, v2
	s_nop 0
	v_mul_f32_e32 v234, v234, v2
	v_mul_f32_e32 v235, v235, v2
	s_waitcnt lgkmcnt(3)
	v_mfma_f32_32x32x16_bf16 v[92:107], v[152:155], v[180:183], v[92:107]
	ds_read_b128 v[152:155], v210 offset:8864
	v_mul_f32_e32 v236, v236, v2
	v_mul_f32_e32 v237, v237, v2
	v_mul_f32_e32 v238, v238, v2
	v_mul_f32_e32 v239, v239, v2
	v_mul_f32_e32 v240, v240, v2
	s_waitcnt lgkmcnt(3)
	v_mfma_f32_32x32x16_bf16 v[92:107], v[156:159], v[184:187], v[92:107]
	ds_read_b128 v[156:159], v210 offset:8896
	v_mul_f32_e32 v241, v241, v2
	v_mul_f32_e32 v242, v242, v2
	v_mul_f32_e32 v243, v243, v2
	v_mul_f32_e32 v244, v244, v2
	v_mul_f32_e32 v245, v245, v2
	v_mul_f32_e32 v246, v246, v2
	s_waitcnt lgkmcnt(3)
	v_mfma_f32_32x32x16_bf16 v[92:107], v[160:163], v[188:191], v[92:107]
	ds_read_b128 v[160:163], v210 offset:8928
	v_mul_f32_e32 v247, v247, v2
	v_mul_f32_e32 v248, v248, v2
	v_mul_f32_e32 v249, v249, v2
	v_mul_f32_e32 v116, v116, v234
	v_mul_f32_e32 v117, v117, v235
	s_waitcnt lgkmcnt(3)
	v_mfma_f32_32x32x16_bf16 v[92:107], v[148:151], v[192:195], v[92:107]
	v_mul_f32_e32 v118, v118, v236
	v_mul_f32_e32 v119, v119, v237
	v_mul_f32_e32 v120, v120, v238
	v_mul_f32_e32 v121, v121, v239
	v_mul_f32_e32 v122, v122, v240
	s_waitcnt lgkmcnt(2)
	v_mfma_f32_32x32x16_bf16 v[92:107], v[152:155], v[196:199], v[92:107]
	v_mul_f32_e32 v123, v123, v241
	v_mul_f32_e32 v124, v124, v242
	v_mul_f32_e32 v125, v125, v243
	v_mul_f32_e32 v126, v126, v244
	v_mul_f32_e32 v127, v127, v245
	v_mul_f32_e32 v128, v128, v246
	s_waitcnt lgkmcnt(1)
	v_mfma_f32_32x32x16_bf16 v[92:107], v[156:159], v[200:203], v[92:107]
	v_mul_f32_e32 v129, v129, v247
	v_mul_f32_e32 v130, v130, v248
	v_mul_f32_e32 v131, v131, v249
	v_cvt_pk_bf16_f32 v116, v116, v117
	v_cvt_pk_bf16_f32 v117, v118, v119
	s_waitcnt lgkmcnt(0)
	v_mfma_f32_32x32x16_bf16 v[92:107], v[160:163], v[204:207], v[92:107]
	v_cvt_pk_bf16_f32 v118, v120, v121
	v_cvt_pk_bf16_f32 v119, v122, v123
	v_cvt_pk_bf16_f32 v120, v124, v125
	v_cvt_pk_bf16_f32 v121, v126, v127
	v_cvt_pk_bf16_f32 v122, v128, v129
	v_cvt_pk_bf16_f32 v123, v130, v131
	v_mfma_f32_32x32x16_bf16 v[76:91], v[36:39], v[116:119], v[76:91]
	v_mfma_f32_32x32x16_bf16 v[76:91], v[72:75], v[120:123], v[76:91]

.Lm_hi_23:
	v_add_u32_e32 v2, s14, v173
	ds_read_b32 v1, v2
	ds_read_b64_tr_b16 v[116:117], v198 offset:0
	ds_read_b64_tr_b16 v[118:119], v198 offset:1088
	ds_read_b64_tr_b16 v[120:121], v192 offset:43008
	ds_read_b64_tr_b16 v[122:123], v192 offset:43264
	ds_read_b64_tr_b16 v[124:125], v198 offset:4352
	ds_read_b64_tr_b16 v[126:127], v198 offset:5440
	ds_read_b64_tr_b16 v[128:129], v192 offset:44032
	ds_read_b64_tr_b16 v[130:131], v192 offset:44288
	ds_read_b64_tr_b16 v[132:133], v198 offset:8704
	ds_read_b64_tr_b16 v[134:135], v198 offset:9792
	ds_read_b64_tr_b16 v[136:137], v192 offset:45056
	ds_read_b64_tr_b16 v[138:139], v192 offset:45312
	s_waitcnt lgkmcnt(12)
	v_exp_f32_e32 v1, v1
	s_nop 0
	v_mul_f32_e32 v176, v176, v1
	v_mul_f32_e32 v177, v177, v1
	v_mul_f32_e32 v178, v178, v1
	v_mul_f32_e32 v179, v179, v1
	v_mul_f32_e32 v180, v180, v1
	v_mul_f32_e32 v181, v181, v1
	v_mul_f32_e32 v182, v182, v1
	v_mul_f32_e32 v183, v183, v1
	v_mul_f32_e32 v184, v184, v1
	v_mul_f32_e32 v185, v185, v1
	v_mul_f32_e32 v186, v186, v1
	v_mul_f32_e32 v187, v187, v1
	v_mul_f32_e32 v188, v188, v1
	v_mul_f32_e32 v189, v189, v1
	v_mul_f32_e32 v190, v190, v1
	v_mul_f32_e32 v191, v191, v1
	s_nop 1
	s_waitcnt lgkmcnt(8)
	v_mfma_f32_32x32x16_bf16 v[176:191], v[116:119], v[120:123], v[176:191]
	ds_read_b64_tr_b16 v[116:117], v198 offset:13056
	ds_read_b64_tr_b16 v[118:119], v198 offset:14144
	ds_read_b64_tr_b16 v[120:121], v192 offset:46080
	ds_read_b64_tr_b16 v[122:123], v192 offset:46336
	s_waitcnt lgkmcnt(8)
	v_mfma_f32_32x32x16_bf16 v[176:191], v[124:127], v[128:131], v[176:191]
	ds_read_b64_tr_b16 v[124:125], v198 offset:17408
	ds_read_b64_tr_b16 v[126:127], v198 offset:18496
	ds_read_b64_tr_b16 v[128:129], v192 offset:47104
	ds_read_b64_tr_b16 v[130:131], v192 offset:47360
	s_waitcnt lgkmcnt(8)
	v_mfma_f32_32x32x16_bf16 v[176:191], v[132:135], v[136:139], v[176:191]
	ds_read_b64_tr_b16 v[132:133], v198 offset:21760
	ds_read_b64_tr_b16 v[134:135], v198 offset:22848
	ds_read_b64_tr_b16 v[136:137], v192 offset:48128
	ds_read_b64_tr_b16 v[138:139], v192 offset:48384
	s_waitcnt lgkmcnt(8)
	v_mfma_f32_32x32x16_bf16 v[176:191], v[116:119], v[120:123], v[176:191]
	ds_read_b64_tr_b16 v[116:117], v198 offset:26112
	ds_read_b64_tr_b16 v[118:119], v198 offset:27200
	ds_read_b64_tr_b16 v[120:121], v192 offset:49152
	ds_read_b64_tr_b16 v[122:123], v192 offset:49408
	s_waitcnt lgkmcnt(8)
	v_mfma_f32_32x32x16_bf16 v[176:191], v[124:127], v[128:131], v[176:191]
	ds_read_b64_tr_b16 v[124:125], v198 offset:30464
	ds_read_b64_tr_b16 v[126:127], v198 offset:31552
	ds_read_b64_tr_b16 v[128:129], v192 offset:50176
	ds_read_b64_tr_b16 v[130:131], v192 offset:50432
	s_waitcnt lgkmcnt(8)
	v_mfma_f32_32x32x16_bf16 v[176:191], v[132:135], v[136:139], v[176:191]
	s_waitcnt lgkmcnt(4)
	v_mfma_f32_32x32x16_bf16 v[176:191], v[116:119], v[120:123], v[176:191]
	s_waitcnt lgkmcnt(0)
	v_mfma_f32_32x32x16_bf16 v[176:191], v[124:127], v[128:131], v[176:191]
	s_nop 7
	s_nop 3
	v_cvt_pk_bf16_f32 v140, v176, v177
	v_cvt_pk_bf16_f32 v141, v178, v179
	v_cvt_pk_bf16_f32 v142, v180, v181
	v_cvt_pk_bf16_f32 v143, v182, v183
	v_cvt_pk_bf16_f32 v144, v184, v185
	v_cvt_pk_bf16_f32 v145, v186, v187
	v_cvt_pk_bf16_f32 v146, v188, v189
	v_cvt_pk_bf16_f32 v147, v190, v191
	ds_write_b64 v194, v[140:141] offset:0
	ds_write_b64 v194, v[142:143] offset:16
	ds_write_b64 v194, v[144:145] offset:32
	ds_write_b64 v194, v[146:147] offset:48
	s_waitcnt vmcnt(10)
	v_add_u32_e32 v154, s16, v172
	v_add_u32_e32 v155, s16, v173
	ds_read_b32 v116, v155
	ds_read_b32 v117, v154
	ds_read_b32 v118, v154 offset:512
	ds_read_b32 v152, v154 offset:256
	ds_read_b32 v153, v154 offset:768
	ds_write_b128 v170, v[4:7] offset:0
	ds_write_b128 v170, v[8:11] offset:272
	ds_write_b128 v170, v[12:15] offset:544
	ds_write_b128 v170, v[16:19] offset:816
	ds_write_b128 v170, v[20:23] offset:1088
	ds_write_b128 v170, v[24:27] offset:1360
	ds_write_b128 v170, v[28:31] offset:1632
	ds_write_b128 v170, v[32:35] offset:1904
	v_lshlrev_b32_e32 v120, 16, v36
	v_and_b32_e32 v121, 0xffff0000, v36
	v_lshlrev_b32_e32 v122, 16, v37
	v_and_b32_e32 v123, 0xffff0000, v37
	v_lshlrev_b32_e32 v124, 16, v38
	v_and_b32_e32 v125, 0xffff0000, v38
	v_lshlrev_b32_e32 v126, 16, v39
	v_and_b32_e32 v127, 0xffff0000, v39
	s_waitcnt lgkmcnt(8)
	v_sub_f32_e32 v119, v116, v117
	v_exp_f32_e32 v119, v119
	v_mul_f32_e32 v128, v118, v120
	v_mul_f32_e32 v129, v118, v121
	v_mul_f32_e32 v130, v118, v122
	v_mul_f32_e32 v131, v118, v123
	v_mul_f32_e32 v132, v118, v124
	v_mul_f32_e32 v133, v118, v125
	v_mul_f32_e32 v134, v118, v126
	v_mul_f32_e32 v135, v118, v127
	v_mul_f32_e32 v119, v118, v119
	v_cvt_pk_bf16_f32 v144, v128, v129
	v_cvt_pk_bf16_f32 v145, v130, v131
	v_cvt_pk_bf16_f32 v146, v132, v133
	v_cvt_pk_bf16_f32 v147, v134, v135
	v_mul_f32_e32 v136, v119, v120
	v_mul_f32_e32 v137, v119, v121
	v_mul_f32_e32 v138, v119, v122
	v_mul_f32_e32 v139, v119, v123
	v_mul_f32_e32 v140, v119, v124
	v_mul_f32_e32 v141, v119, v125
	v_mul_f32_e32 v142, v119, v126
	v_mul_f32_e32 v143, v119, v127
	v_cvt_pk_bf16_f32 v148, v136, v137
	v_cvt_pk_bf16_f32 v149, v138, v139
	v_cvt_pk_bf16_f32 v150, v140, v141
	v_cvt_pk_bf16_f32 v151, v142, v143
	ds_write_b128 v171, v[144:147] offset:0
	ds_write_b128 v197, v[148:151] offset:0
	v_lshlrev_b32_e32 v120, 16, v40
	v_and_b32_e32 v121, 0xffff0000, v40
	v_lshlrev_b32_e32 v122, 16, v41
	v_and_b32_e32 v123, 0xffff0000, v41
	v_lshlrev_b32_e32 v124, 16, v42
	v_and_b32_e32 v125, 0xffff0000, v42
	v_lshlrev_b32_e32 v126, 16, v43
	v_and_b32_e32 v127, 0xffff0000, v43
	v_sub_f32_e32 v119, v116, v152
	v_exp_f32_e32 v119, v119
	v_mul_f32_e32 v128, v153, v120
	v_mul_f32_e32 v129, v153, v121
	v_mul_f32_e32 v130, v153, v122
	v_mul_f32_e32 v131, v153, v123
	v_mul_f32_e32 v132, v153, v124
	v_mul_f32_e32 v133, v153, v125
	v_mul_f32_e32 v134, v153, v126
	v_mul_f32_e32 v135, v153, v127
	v_mul_f32_e32 v119, v153, v119
	v_cvt_pk_bf16_f32 v144, v128, v129
	v_cvt_pk_bf16_f32 v145, v130, v131
	v_cvt_pk_bf16_f32 v146, v132, v133
	v_cvt_pk_bf16_f32 v147, v134, v135
	v_mul_f32_e32 v136, v119, v120
	v_mul_f32_e32 v137, v119, v121
	v_mul_f32_e32 v138, v119, v122
	v_mul_f32_e32 v139, v119, v123
	v_mul_f32_e32 v140, v119, v124
	v_mul_f32_e32 v141, v119, v125
	v_mul_f32_e32 v142, v119, v126
	v_mul_f32_e32 v143, v119, v127
	v_cvt_pk_bf16_f32 v148, v136, v137
	v_cvt_pk_bf16_f32 v149, v138, v139
	v_cvt_pk_bf16_f32 v150, v140, v141
	v_cvt_pk_bf16_f32 v151, v142, v143
	ds_write_b128 v171, v[144:147] offset:4096
	ds_write_b128 v197, v[148:151] offset:4096
	global_load_dwordx4 v[4:7], v164, s[38:39] offset:0
	global_load_dwordx4 v[8:11], v164, s[38:39] offset:512
	global_load_dwordx4 v[12:15], v164, s[38:39] offset:1024
	global_load_dwordx4 v[16:19], v164, s[38:39] offset:1536
	global_load_dwordx4 v[20:23], v164, s[38:39] offset:2048
	global_load_dwordx4 v[24:27], v164, s[38:39] offset:2560
	global_load_dwordx4 v[28:31], v164, s[38:39] offset:3072
	global_load_dwordx4 v[32:35], v164, s[38:39] offset:3584
	global_load_dwordx4 v[36:39], v168, s[40:41]
	global_load_dwordx4 v[40:43], v169, s[40:41]
	s_add_u32 s38, s38, s46
	s_addc_u32 s39, s39, s55
	s_add_u32 s40, s40, s47
	s_addc_u32 s41, s41, s55
.Lm_stepdone_24:
	s_waitcnt lgkmcnt(0)
	s_barrier
	s_mov_b32 s14, s16
	s_mov_b32 s16, s17
	s_add_u32 s17, s17, 1280
	s_cmpk_eq_u32 s17, 5120
	s_cselect_b32 s17, 0, s17
	s_add_u32 s50, s50, 1
	s_cmp_lt_u32 s50, 64
	s_cbranch_scc1 .Lm_loop
	s_cmp_lt_u32 s3, 4
	s_cbranch_scc0 .Lm_noflush_33
	s_nop 7
	s_nop 3
	v_fma_f32 v76, v92, v3, v76
	v_fma_f32 v77, v93, v3, v77
	v_fma_f32 v78, v94, v3, v78
	v_fma_f32 v79, v95, v3, v79
	v_fma_f32 v80, v96, v3, v80
	v_fma_f32 v81, v97, v3, v81
	v_fma_f32 v82, v98, v3, v82
	v_fma_f32 v83, v99, v3, v83
	v_fma_f32 v84, v100, v3, v84
	v_fma_f32 v85, v101, v3, v85
	v_fma_f32 v86, v102, v3, v86
	v_fma_f32 v87, v103, v3, v87
	v_fma_f32 v88, v104, v3, v88
	v_fma_f32 v89, v105, v3, v89
	v_fma_f32 v90, v106, v3, v90
	v_fma_f32 v91, v107, v3, v91
	v_cvt_pk_bf16_f32 v36, v76, v77
	v_cvt_pk_bf16_f32 v37, v78, v79
	v_cvt_pk_bf16_f32 v38, v80, v81
	v_cvt_pk_bf16_f32 v39, v82, v83
	v_cvt_pk_bf16_f32 v72, v84, v85
	v_cvt_pk_bf16_f32 v73, v86, v87
	v_cvt_pk_bf16_f32 v74, v88, v89
	v_cvt_pk_bf16_f32 v75, v90, v91
	ds_write_b64 v168, v[36:37] offset:0
	ds_write_b64 v168, v[38:39] offset:16
	ds_write_b64 v168, v[72:73] offset:32
	ds_write_b64 v168, v[74:75] offset:48
	s_waitcnt lgkmcnt(0)
	ds_read_b128 v[92:95], v169
	ds_read_b128 v[96:99], v169 offset:1280
	s_waitcnt lgkmcnt(0)
	global_store_dwordx4 v170, v[92:95], s[44:45]
	global_store_dwordx4 v171, v[96:99], s[44:45]
.Lm_noflush_33:
	s_waitcnt vmcnt(0)
	s_add_u32 s61, s61, s58
	s_cmpk_gt_i32 s61, 0xff
	s_cbranch_scc0 .Lm_item
	s_mov_b32 s77, 0x800000
